# v19 + 2 wait states between each v_cmp_e64 SGPR-pair write and the v_cndmask that reads it as mask (hazard padding in the combined-atomics tail)
# speedup vs baseline: 1.0031x; 1.0031x over previous
; #define PG8_LAS __attribute__((address_space(3)))
; __device__ __forceinline__ unsigned cvt_pk_bf16(float lo, float hi) { unsigned r; asm volatile("v_cvt_pk_bf16_f32 %0, %1, %2" : "=v"(r) : "v"(lo), "v"(hi)); return r; }
;     __device__ __forceinline__ void operator()(const f32x4 (&acc)[2][2][4][2], const Unit& u, int wr, int wc, int fr, int fq) const {
;     ...
;                 for (int bj = 0; bj < 2; ++bj) {
;                     const size_t off = (size_t)row * 2048 + u.pn * BM + wc * 64 + bj * 32 + 8 * p;
;                     f32x4 b0, b1;
;                     if (BASE_F32) { b0 = *(const f32x4*)((const float*)base + off); b1 = *(const f32x4*)((const float*)base + off + 4); }
;                     else { const u32x4 bb = *(const u32x4*)((const bf16_t*)base + off);
;                         b0 = (f32x4){__uint_as_float(bb.x << 16), __uint_as_float(bb.x & 0xffff0000u), __uint_as_float(bb.y << 16), __uint_as_float(bb.y & 0xffff0000u)};
;                         b1 = (f32x4){__uint_as_float(bb.z << 16), __uint_as_float(bb.z & 0xffff0000u), __uint_as_float(bb.w << 16), __uint_as_float(bb.w & 0xffff0000u)}; }
; #pragma unroll
;                     for (int n = 0; n < 2; ++n) *(PG8_LAS f32x4*)(stg + fr * STG_ROW + n * 64 + fq * 16) = acc[ai][bj][m][n];
;                     const f32x4 v0 = *(const PG8_LAS f32x4*)(stg + r * STG_ROW + p * 32) + b0, v1 = *(const PG8_LAS f32x4*)(stg + r * STG_ROW + p * 32 + 16) + b1;
;                     q += ((v0[0] * v0[0] + v0[1] * v0[1]) + (v0[2] * v0[2] + v0[3] * v0[3])) + ((v1[0] * v1[0] + v1[1] * v1[1]) + (v1[2] * v1[2] + v1[3] * v1[3]));
;                     u32x4 w; w.x = cvt_pk_bf16(v0[0], v0[1]); w.y = cvt_pk_bf16(v0[2], v0[3]); w.z = cvt_pk_bf16(v1[0], v1[1]); w.w = cvt_pk_bf16(v1[2], v1[3]);
;                     *(u32x4*)(out + off) = w;
;                 }
;                 q += __shfl_xor(q, 1); q += __shfl_xor(q, 2);
;                 if (p == 0) atomicAdd(ssn + row, (u64)(q * SS_SCALE));
.LBB0_295:
	ds_write_b128 v156, v[124:127]
	ds_write_b128 v156, v[120:123] offset:64
	ds_read_b128 v[120:123], v157
	ds_read_b128 v[124:127], v157 offset:16
	ds_write_b128 v156, v[116:119]
	ds_write_b128 v156, v[112:115] offset:64
	ds_read_b128 v[112:115], v157
	ds_read_b128 v[116:119], v157 offset:16
	s_waitcnt vmcnt(18) lgkmcnt(4)
	v_pk_add_f32 v[120:121], v[160:161], v[120:121]
	v_pk_add_f32 v[122:123], v[162:163], v[122:123]
	v_pk_add_f32 v[124:125], v[164:165], v[124:125]
	v_pk_add_f32 v[126:127], v[166:167], v[126:127]
	v_add_u32_e32 v149, 0x120000, v158
	global_load_dwordx4 v[160:163], v149, s[12:13]
	global_load_dwordx4 v[164:167], v149, s[12:13] offset:16
	v_mul_f32_e32 v244, v121, v121
	v_mul_f32_e32 v245, v123, v123
	v_mul_f32_e32 v246, v125, v125
	v_mul_f32_e32 v247, v127, v127
	v_fmac_f32_e32 v244, v120, v120
	v_fmac_f32_e32 v245, v122, v122
	v_fmac_f32_e32 v246, v124, v124
	v_fmac_f32_e32 v247, v126, v126
	v_cvt_pk_bf16_f32 v120, v120, v121
	v_cvt_pk_bf16_f32 v121, v122, v123
	v_cvt_pk_bf16_f32 v122, v124, v125
	v_cvt_pk_bf16_f32 v123, v126, v127
	v_add_f32_e32 v244, v244, v245
	v_add_f32_e32 v245, v246, v247
	v_add_f32_e32 v124, v244, v245
	global_store_dwordx4 v159, v[120:123], s[38:39]
	ds_write_b128 v156, v[108:111]
	ds_write_b128 v156, v[104:107] offset:64
	ds_read_b128 v[104:107], v157
	ds_read_b128 v[108:111], v157 offset:16
	s_waitcnt vmcnt(19) lgkmcnt(4)
	v_pk_add_f32 v[112:113], v[168:169], v[112:113]
	v_pk_add_f32 v[114:115], v[170:171], v[114:115]
	v_pk_add_f32 v[116:117], v[172:173], v[116:117]
	v_pk_add_f32 v[118:119], v[174:175], v[118:119]
	global_load_dwordx4 v[168:171], v149, s[12:13] offset:128
	global_load_dwordx4 v[172:175], v149, s[12:13] offset:144
	v_mul_f32_e32 v244, v113, v113
	v_mul_f32_e32 v245, v115, v115
	v_mul_f32_e32 v246, v117, v117
	v_mul_f32_e32 v247, v119, v119
	v_fmac_f32_e32 v244, v112, v112
	v_fmac_f32_e32 v245, v114, v114
	v_fmac_f32_e32 v246, v116, v116
	v_fmac_f32_e32 v247, v118, v118
	v_cvt_pk_bf16_f32 v112, v112, v113
	v_cvt_pk_bf16_f32 v113, v114, v115
	v_cvt_pk_bf16_f32 v114, v116, v117
	v_cvt_pk_bf16_f32 v115, v118, v119
	v_add_f32_e32 v244, v244, v245
	v_add_f32_e32 v245, v246, v247
	v_add_f32_e32 v116, v244, v245
	global_store_dwordx4 v159, v[112:115], s[38:39] offset:64
	v_add_f32_e32 v117, v124, v116
	s_nop 1
	v_add_f32_dpp v118, v117, v117 quad_perm:[1,0,3,2] row_mask:0xf bank_mask:0xf
	s_nop 1
	v_add_f32_dpp v119, v118, v118 quad_perm:[2,3,0,1] row_mask:0xf bank_mask:0xf
	v_mul_f32_e32 v126, 0x49800000, v119
	v_trunc_f32_e32 v126, v126
	v_mul_f32_e32 v127, 0x2f800000, v126
	v_floor_f32_e32 v127, v127
	v_fmac_f32_e32 v126, 0xcf800000, v127
	v_cvt_u32_f32_e32 v126, v126
	v_cvt_u32_f32_e32 v127, v127
	ds_write_b128 v156, v[100:103]
	ds_write_b128 v156, v[96:99] offset:64
	ds_read_b128 v[96:99], v157
	ds_read_b128 v[100:103], v157 offset:16
	s_waitcnt vmcnt(20) lgkmcnt(4)
	v_pk_add_f32 v[104:105], v[176:177], v[104:105]
	v_pk_add_f32 v[106:107], v[178:179], v[106:107]
	v_pk_add_f32 v[108:109], v[180:181], v[108:109]
	v_pk_add_f32 v[110:111], v[182:183], v[110:111]
	v_add_u32_e32 v209, 0x140000, v158
	global_load_dwordx4 v[176:179], v209, s[12:13]
	global_load_dwordx4 v[180:183], v209, s[12:13] offset:16
	v_mul_f32_e32 v244, v105, v105
	v_mul_f32_e32 v245, v107, v107
	v_mul_f32_e32 v246, v109, v109
	v_mul_f32_e32 v247, v111, v111
	v_fmac_f32_e32 v244, v104, v104
	v_fmac_f32_e32 v245, v106, v106
	v_fmac_f32_e32 v246, v108, v108
	v_fmac_f32_e32 v247, v110, v110
	v_cvt_pk_bf16_f32 v104, v104, v105
	v_cvt_pk_bf16_f32 v105, v106, v107
	v_cvt_pk_bf16_f32 v106, v108, v109
	v_cvt_pk_bf16_f32 v107, v110, v111
	v_add_f32_e32 v244, v244, v245
	v_add_f32_e32 v245, v246, v247
	v_add_f32_e32 v108, v244, v245
	v_add_u32_e32 v147, 0x10000, v159
	global_store_dwordx4 v147, v[104:107], s[38:39]
	ds_write_b128 v156, v[92:95]
	ds_write_b128 v156, v[88:91] offset:64
	ds_read_b128 v[88:91], v157
	ds_read_b128 v[92:95], v157 offset:16
	s_waitcnt vmcnt(21) lgkmcnt(4)
	v_pk_add_f32 v[96:97], v[184:185], v[96:97]
	v_pk_add_f32 v[98:99], v[186:187], v[98:99]
	v_pk_add_f32 v[100:101], v[188:189], v[100:101]
	v_pk_add_f32 v[102:103], v[190:191], v[102:103]
	global_load_dwordx4 v[184:187], v209, s[12:13] offset:128
	global_load_dwordx4 v[188:191], v209, s[12:13] offset:144
	v_mul_f32_e32 v244, v97, v97
	v_mul_f32_e32 v245, v99, v99
	v_mul_f32_e32 v246, v101, v101
	v_mul_f32_e32 v247, v103, v103
	v_fmac_f32_e32 v244, v96, v96
	v_fmac_f32_e32 v245, v98, v98
	v_fmac_f32_e32 v246, v100, v100
	v_fmac_f32_e32 v247, v102, v102
	v_cvt_pk_bf16_f32 v96, v96, v97
	v_cvt_pk_bf16_f32 v97, v98, v99
	v_cvt_pk_bf16_f32 v98, v100, v101
	v_cvt_pk_bf16_f32 v99, v102, v103
	v_add_f32_e32 v244, v244, v245
	v_add_f32_e32 v245, v246, v247
	v_add_f32_e32 v100, v244, v245
	global_store_dwordx4 v147, v[96:99], s[38:39] offset:64
	v_add_f32_e32 v101, v108, v100
	s_nop 1
	v_add_f32_dpp v102, v101, v101 quad_perm:[1,0,3,2] row_mask:0xf bank_mask:0xf
	s_nop 1
	v_add_f32_dpp v103, v102, v102 quad_perm:[2,3,0,1] row_mask:0xf bank_mask:0xf
	v_mul_f32_e32 v110, 0x49800000, v103
	v_trunc_f32_e32 v110, v110
	v_mul_f32_e32 v111, 0x2f800000, v110
	v_floor_f32_e32 v111, v111
	v_fmac_f32_e32 v110, 0xcf800000, v111
	v_cvt_u32_f32_e32 v110, v110
	v_cvt_u32_f32_e32 v111, v111
	ds_write_b128 v156, v[84:87]
	ds_write_b128 v156, v[80:83] offset:64
	ds_read_b128 v[80:83], v157
	ds_read_b128 v[84:87], v157 offset:16
	s_waitcnt vmcnt(22) lgkmcnt(4)
; #define PG8_LAS __attribute__((address_space(3)))
; __device__ __forceinline__ unsigned cvt_pk_bf16(float lo, float hi) { unsigned r; asm volatile("v_cvt_pk_bf16_f32 %0, %1, %2" : "=v"(r) : "v"(lo), "v"(hi)); return r; }
;     __device__ __forceinline__ void operator()(const f32x4 (&acc)[2][2][4][2], const Unit& u, int wr, int wc, int fr, int fq) const {
;     ...
;                 for (int bj = 0; bj < 2; ++bj) {
;                     const size_t off = (size_t)row * 2048 + u.pn * BM + wc * 64 + bj * 32 + 8 * p;
;                     f32x4 b0, b1;
;                     if (BASE_F32) { b0 = *(const f32x4*)((const float*)base + off); b1 = *(const f32x4*)((const float*)base + off + 4); }
;                     else { const u32x4 bb = *(const u32x4*)((const bf16_t*)base + off);
;                         b0 = (f32x4){__uint_as_float(bb.x << 16), __uint_as_float(bb.x & 0xffff0000u), __uint_as_float(bb.y << 16), __uint_as_float(bb.y & 0xffff0000u)};
;                         b1 = (f32x4){__uint_as_float(bb.z << 16), __uint_as_float(bb.z & 0xffff0000u), __uint_as_float(bb.w << 16), __uint_as_float(bb.w & 0xffff0000u)}; }
; #pragma unroll
;                     for (int n = 0; n < 2; ++n) *(PG8_LAS f32x4*)(stg + fr * STG_ROW + n * 64 + fq * 16) = acc[ai][bj][m][n];
;                     const f32x4 v0 = *(const PG8_LAS f32x4*)(stg + r * STG_ROW + p * 32) + b0, v1 = *(const PG8_LAS f32x4*)(stg + r * STG_ROW + p * 32 + 16) + b1;
;                     q += ((v0[0] * v0[0] + v0[1] * v0[1]) + (v0[2] * v0[2] + v0[3] * v0[3])) + ((v1[0] * v1[0] + v1[1] * v1[1]) + (v1[2] * v1[2] + v1[3] * v1[3]));
;                     u32x4 w; w.x = cvt_pk_bf16(v0[0], v0[1]); w.y = cvt_pk_bf16(v0[2], v0[3]); w.z = cvt_pk_bf16(v1[0], v1[1]); w.w = cvt_pk_bf16(v1[2], v1[3]);
;                     *(u32x4*)(out + off) = w;
;                 }
;                 q += __shfl_xor(q, 1); q += __shfl_xor(q, 2);
;                 if (p == 0) atomicAdd(ssn + row, (u64)(q * SS_SCALE));
	v_pk_add_f32 v[88:89], v[192:193], v[88:89]
	v_pk_add_f32 v[90:91], v[194:195], v[90:91]
	v_pk_add_f32 v[92:93], v[196:197], v[92:93]
	v_pk_add_f32 v[94:95], v[198:199], v[94:95]
	v_add_u32_e32 v149, 0x160000, v158
	global_load_dwordx4 v[192:195], v149, s[12:13]
	global_load_dwordx4 v[196:199], v149, s[12:13] offset:16
	v_mul_f32_e32 v244, v89, v89
	v_mul_f32_e32 v245, v91, v91
	v_mul_f32_e32 v246, v93, v93
	v_mul_f32_e32 v247, v95, v95
	v_fmac_f32_e32 v244, v88, v88
	v_fmac_f32_e32 v245, v90, v90
	v_fmac_f32_e32 v246, v92, v92
	v_fmac_f32_e32 v247, v94, v94
	v_cvt_pk_bf16_f32 v88, v88, v89
	v_cvt_pk_bf16_f32 v89, v90, v91
	v_cvt_pk_bf16_f32 v90, v92, v93
	v_cvt_pk_bf16_f32 v91, v94, v95
	v_add_f32_e32 v244, v244, v245
	v_add_f32_e32 v245, v246, v247
	v_add_f32_e32 v92, v244, v245
	v_add_u32_e32 v146, 0x20000, v159
	global_store_dwordx4 v146, v[88:91], s[38:39]
	ds_write_b128 v156, v[76:79]
	ds_write_b128 v156, v[72:75] offset:64
	ds_read_b128 v[72:75], v157
	ds_read_b128 v[76:79], v157 offset:16
	s_waitcnt vmcnt(23) lgkmcnt(4)
	v_pk_add_f32 v[80:81], v[200:201], v[80:81]
	v_pk_add_f32 v[82:83], v[202:203], v[82:83]
	v_pk_add_f32 v[84:85], v[204:205], v[84:85]
	v_pk_add_f32 v[86:87], v[206:207], v[86:87]
	global_load_dwordx4 v[200:203], v149, s[12:13] offset:128
	global_load_dwordx4 v[204:207], v149, s[12:13] offset:144
	v_mul_f32_e32 v244, v81, v81
	v_mul_f32_e32 v245, v83, v83
	v_mul_f32_e32 v246, v85, v85
	v_mul_f32_e32 v247, v87, v87
	v_fmac_f32_e32 v244, v80, v80
	v_fmac_f32_e32 v245, v82, v82
	v_fmac_f32_e32 v246, v84, v84
	v_fmac_f32_e32 v247, v86, v86
	v_cvt_pk_bf16_f32 v80, v80, v81
	v_cvt_pk_bf16_f32 v81, v82, v83
	v_cvt_pk_bf16_f32 v82, v84, v85
	v_cvt_pk_bf16_f32 v83, v86, v87
	v_add_f32_e32 v244, v244, v245
	v_add_f32_e32 v245, v246, v247
	v_add_f32_e32 v84, v244, v245
	global_store_dwordx4 v146, v[80:83], s[38:39] offset:64
	v_add_f32_e32 v85, v92, v84
	s_nop 1
	v_add_f32_dpp v86, v85, v85 quad_perm:[1,0,3,2] row_mask:0xf bank_mask:0xf
	s_nop 1
	v_add_f32_dpp v87, v86, v86 quad_perm:[2,3,0,1] row_mask:0xf bank_mask:0xf
	v_mul_f32_e32 v94, 0x49800000, v87
	v_trunc_f32_e32 v94, v94
	v_mul_f32_e32 v95, 0x2f800000, v94
	v_floor_f32_e32 v95, v95
	v_fmac_f32_e32 v94, 0xcf800000, v95
	v_cvt_u32_f32_e32 v94, v94
	v_cvt_u32_f32_e32 v95, v95
	ds_write_b128 v156, v[68:71]
	ds_write_b128 v156, v[64:67] offset:64
	ds_read_b128 v[64:67], v157
	ds_read_b128 v[68:71], v157 offset:16
	s_waitcnt vmcnt(24) lgkmcnt(4)
	v_pk_add_f32 v[72:73], v[212:213], v[72:73]
	v_pk_add_f32 v[74:75], v[214:215], v[74:75]
	v_pk_add_f32 v[76:77], v[216:217], v[76:77]
	v_pk_add_f32 v[78:79], v[218:219], v[78:79]
	v_mul_f32_e32 v244, v73, v73
	v_mul_f32_e32 v245, v75, v75
	v_mul_f32_e32 v246, v77, v77
	v_mul_f32_e32 v247, v79, v79
	v_fmac_f32_e32 v244, v72, v72
	v_fmac_f32_e32 v245, v74, v74
	v_fmac_f32_e32 v246, v76, v76
	v_fmac_f32_e32 v247, v78, v78
	v_cvt_pk_bf16_f32 v72, v72, v73
	v_cvt_pk_bf16_f32 v73, v74, v75
	v_cvt_pk_bf16_f32 v74, v76, v77
	v_cvt_pk_bf16_f32 v75, v78, v79
	v_add_f32_e32 v244, v244, v245
	v_add_f32_e32 v245, v246, v247
	v_add_f32_e32 v76, v244, v245
	v_add_u32_e32 v147, 0x30000, v159
	global_store_dwordx4 v147, v[72:75], s[38:39]
	ds_write_b128 v156, v[60:63]
	ds_write_b128 v156, v[56:59] offset:64
	ds_read_b128 v[56:59], v157
	ds_read_b128 v[60:63], v157 offset:16
	s_waitcnt vmcnt(23) lgkmcnt(4)
	v_pk_add_f32 v[64:65], v[220:221], v[64:65]
	v_pk_add_f32 v[66:67], v[222:223], v[66:67]
	v_pk_add_f32 v[68:69], v[224:225], v[68:69]
	v_pk_add_f32 v[70:71], v[226:227], v[70:71]
	v_mul_f32_e32 v244, v65, v65
	v_mul_f32_e32 v245, v67, v67
	v_mul_f32_e32 v246, v69, v69
	v_mul_f32_e32 v247, v71, v71
	v_fmac_f32_e32 v244, v64, v64
	v_fmac_f32_e32 v245, v66, v66
	v_fmac_f32_e32 v246, v68, v68
	v_fmac_f32_e32 v247, v70, v70
	v_cvt_pk_bf16_f32 v64, v64, v65
	v_cvt_pk_bf16_f32 v65, v66, v67
	v_cvt_pk_bf16_f32 v66, v68, v69
	v_cvt_pk_bf16_f32 v67, v70, v71
	v_add_f32_e32 v244, v244, v245
	v_add_f32_e32 v245, v246, v247
	v_add_f32_e32 v68, v244, v245
	global_store_dwordx4 v147, v[64:67], s[38:39] offset:64
	v_add_f32_e32 v69, v76, v68
	s_nop 1
	v_add_f32_dpp v70, v69, v69 quad_perm:[1,0,3,2] row_mask:0xf bank_mask:0xf
	s_nop 1
	v_add_f32_dpp v71, v70, v70 quad_perm:[2,3,0,1] row_mask:0xf bank_mask:0xf
	v_mul_f32_e32 v78, 0x49800000, v71
	v_trunc_f32_e32 v78, v78
	v_mul_f32_e32 v79, 0x2f800000, v78
	v_floor_f32_e32 v79, v79
	v_fmac_f32_e32 v78, 0xcf800000, v79
	v_cvt_u32_f32_e32 v78, v78
	v_cvt_u32_f32_e32 v79, v79
	ds_write_b128 v156, v[52:55]
	ds_write_b128 v156, v[48:51] offset:64
	ds_read_b128 v[48:51], v157
	ds_read_b128 v[52:55], v157 offset:16
	s_waitcnt vmcnt(22) lgkmcnt(4)
	v_pk_add_f32 v[56:57], v[228:229], v[56:57]
	v_pk_add_f32 v[58:59], v[230:231], v[58:59]
	v_pk_add_f32 v[60:61], v[232:233], v[60:61]
	v_pk_add_f32 v[62:63], v[234:235], v[62:63]
	v_mul_f32_e32 v244, v57, v57
	v_mul_f32_e32 v245, v59, v59
	v_mul_f32_e32 v246, v61, v61
	v_mul_f32_e32 v247, v63, v63
	v_fmac_f32_e32 v244, v56, v56
	v_fmac_f32_e32 v245, v58, v58
	v_fmac_f32_e32 v246, v60, v60
	v_fmac_f32_e32 v247, v62, v62
	v_cvt_pk_bf16_f32 v56, v56, v57
	v_cvt_pk_bf16_f32 v57, v58, v59
	v_cvt_pk_bf16_f32 v58, v60, v61
	v_cvt_pk_bf16_f32 v59, v62, v63
	v_add_f32_e32 v244, v244, v245
	v_add_f32_e32 v245, v246, v247
	v_add_f32_e32 v60, v244, v245
	v_add_u32_e32 v146, 0x80000, v159
	global_store_dwordx4 v146, v[56:59], s[38:39]
	ds_write_b128 v156, v[44:47]
	ds_write_b128 v156, v[40:43] offset:64
	ds_read_b128 v[40:43], v157
	ds_read_b128 v[44:47], v157 offset:16
	s_waitcnt vmcnt(21) lgkmcnt(4)
; #define PG8_LAS __attribute__((address_space(3)))
; __device__ __forceinline__ unsigned cvt_pk_bf16(float lo, float hi) { unsigned r; asm volatile("v_cvt_pk_bf16_f32 %0, %1, %2" : "=v"(r) : "v"(lo), "v"(hi)); return r; }
;     __device__ __forceinline__ void operator()(const f32x4 (&acc)[2][2][4][2], const Unit& u, int wr, int wc, int fr, int fq) const {
;     ...
;                 for (int bj = 0; bj < 2; ++bj) {
;                     const size_t off = (size_t)row * 2048 + u.pn * BM + wc * 64 + bj * 32 + 8 * p;
;                     f32x4 b0, b1;
;                     if (BASE_F32) { b0 = *(const f32x4*)((const float*)base + off); b1 = *(const f32x4*)((const float*)base + off + 4); }
;                     else { const u32x4 bb = *(const u32x4*)((const bf16_t*)base + off);
;                         b0 = (f32x4){__uint_as_float(bb.x << 16), __uint_as_float(bb.x & 0xffff0000u), __uint_as_float(bb.y << 16), __uint_as_float(bb.y & 0xffff0000u)};
;                         b1 = (f32x4){__uint_as_float(bb.z << 16), __uint_as_float(bb.z & 0xffff0000u), __uint_as_float(bb.w << 16), __uint_as_float(bb.w & 0xffff0000u)}; }
; #pragma unroll
;                     for (int n = 0; n < 2; ++n) *(PG8_LAS f32x4*)(stg + fr * STG_ROW + n * 64 + fq * 16) = acc[ai][bj][m][n];
;                     const f32x4 v0 = *(const PG8_LAS f32x4*)(stg + r * STG_ROW + p * 32) + b0, v1 = *(const PG8_LAS f32x4*)(stg + r * STG_ROW + p * 32 + 16) + b1;
;                     q += ((v0[0] * v0[0] + v0[1] * v0[1]) + (v0[2] * v0[2] + v0[3] * v0[3])) + ((v1[0] * v1[0] + v1[1] * v1[1]) + (v1[2] * v1[2] + v1[3] * v1[3]));
;                     u32x4 w; w.x = cvt_pk_bf16(v0[0], v0[1]); w.y = cvt_pk_bf16(v0[2], v0[3]); w.z = cvt_pk_bf16(v1[0], v1[1]); w.w = cvt_pk_bf16(v1[2], v1[3]);
;                     *(u32x4*)(out + off) = w;
;                 }
;                 q += __shfl_xor(q, 1); q += __shfl_xor(q, 2);
;                 if (p == 0) atomicAdd(ssn + row, (u64)(q * SS_SCALE));
	v_pk_add_f32 v[48:49], v[236:237], v[48:49]
	v_pk_add_f32 v[50:51], v[238:239], v[50:51]
	v_pk_add_f32 v[52:53], v[240:241], v[52:53]
	v_pk_add_f32 v[54:55], v[242:243], v[54:55]
	v_mul_f32_e32 v244, v49, v49
	v_mul_f32_e32 v245, v51, v51
	v_mul_f32_e32 v246, v53, v53
	v_mul_f32_e32 v247, v55, v55
	v_fmac_f32_e32 v244, v48, v48
	v_fmac_f32_e32 v245, v50, v50
	v_fmac_f32_e32 v246, v52, v52
	v_fmac_f32_e32 v247, v54, v54
	v_cvt_pk_bf16_f32 v48, v48, v49
	v_cvt_pk_bf16_f32 v49, v50, v51
	v_cvt_pk_bf16_f32 v50, v52, v53
	v_cvt_pk_bf16_f32 v51, v54, v55
	v_add_f32_e32 v244, v244, v245
	v_add_f32_e32 v245, v246, v247
	v_add_f32_e32 v52, v244, v245
	global_store_dwordx4 v146, v[48:51], s[38:39] offset:64
	v_add_f32_e32 v53, v60, v52
	s_nop 1
	v_add_f32_dpp v54, v53, v53 quad_perm:[1,0,3,2] row_mask:0xf bank_mask:0xf
	s_nop 1
	v_add_f32_dpp v55, v54, v54 quad_perm:[2,3,0,1] row_mask:0xf bank_mask:0xf
	v_mul_f32_e32 v62, 0x49800000, v55
	v_trunc_f32_e32 v62, v62
	v_mul_f32_e32 v63, 0x2f800000, v62
	v_floor_f32_e32 v63, v63
	v_fmac_f32_e32 v62, 0xcf800000, v63
	v_cvt_u32_f32_e32 v62, v62
	v_cvt_u32_f32_e32 v63, v63
	ds_write_b128 v156, v[36:39]
	ds_write_b128 v156, v[32:35] offset:64
	ds_read_b128 v[32:35], v157
	ds_read_b128 v[36:39], v157 offset:16
	s_waitcnt vmcnt(20) lgkmcnt(4)
	v_pk_add_f32 v[40:41], v[160:161], v[40:41]
	v_pk_add_f32 v[42:43], v[162:163], v[42:43]
	v_pk_add_f32 v[44:45], v[164:165], v[44:45]
	v_pk_add_f32 v[46:47], v[166:167], v[46:47]
	v_mul_f32_e32 v244, v41, v41
	v_mul_f32_e32 v245, v43, v43
	v_mul_f32_e32 v246, v45, v45
	v_mul_f32_e32 v247, v47, v47
	v_fmac_f32_e32 v244, v40, v40
	v_fmac_f32_e32 v245, v42, v42
	v_fmac_f32_e32 v246, v44, v44
	v_fmac_f32_e32 v247, v46, v46
	v_cvt_pk_bf16_f32 v40, v40, v41
	v_cvt_pk_bf16_f32 v41, v42, v43
	v_cvt_pk_bf16_f32 v42, v44, v45
	v_cvt_pk_bf16_f32 v43, v46, v47
	v_add_f32_e32 v244, v244, v245
	v_add_f32_e32 v245, v246, v247
	v_add_f32_e32 v44, v244, v245
	v_add_u32_e32 v147, 0x90000, v159
	global_store_dwordx4 v147, v[40:43], s[38:39]
	ds_write_b128 v156, v[28:31]
	ds_write_b128 v156, v[24:27] offset:64
	ds_read_b128 v[24:27], v157
	ds_read_b128 v[28:31], v157 offset:16
	s_waitcnt vmcnt(18) lgkmcnt(4)
	v_pk_add_f32 v[32:33], v[168:169], v[32:33]
	v_pk_add_f32 v[34:35], v[170:171], v[34:35]
	v_pk_add_f32 v[36:37], v[172:173], v[36:37]
	v_pk_add_f32 v[38:39], v[174:175], v[38:39]
	v_mul_f32_e32 v244, v33, v33
	v_mul_f32_e32 v245, v35, v35
	v_mul_f32_e32 v246, v37, v37
	v_mul_f32_e32 v247, v39, v39
	v_fmac_f32_e32 v244, v32, v32
	v_fmac_f32_e32 v245, v34, v34
	v_fmac_f32_e32 v246, v36, v36
	v_fmac_f32_e32 v247, v38, v38
	v_cvt_pk_bf16_f32 v32, v32, v33
	v_cvt_pk_bf16_f32 v33, v34, v35
	v_cvt_pk_bf16_f32 v34, v36, v37
	v_cvt_pk_bf16_f32 v35, v38, v39
	v_add_f32_e32 v244, v244, v245
	v_add_f32_e32 v245, v246, v247
	v_add_f32_e32 v36, v244, v245
	global_store_dwordx4 v147, v[32:35], s[38:39] offset:64
	v_add_f32_e32 v37, v44, v36
	s_nop 1
	v_add_f32_dpp v38, v37, v37 quad_perm:[1,0,3,2] row_mask:0xf bank_mask:0xf
	s_nop 1
	v_add_f32_dpp v39, v38, v38 quad_perm:[2,3,0,1] row_mask:0xf bank_mask:0xf
	v_mul_f32_e32 v46, 0x49800000, v39
	v_trunc_f32_e32 v46, v46
	v_mul_f32_e32 v47, 0x2f800000, v46
	v_floor_f32_e32 v47, v47
	v_fmac_f32_e32 v46, 0xcf800000, v47
	v_cvt_u32_f32_e32 v46, v46
	v_cvt_u32_f32_e32 v47, v47
	ds_write_b128 v156, v[20:23]
	ds_write_b128 v156, v[16:19] offset:64
	ds_read_b128 v[16:19], v157
	ds_read_b128 v[20:23], v157 offset:16
	s_waitcnt vmcnt(16) lgkmcnt(4)
	v_pk_add_f32 v[24:25], v[176:177], v[24:25]
	v_pk_add_f32 v[26:27], v[178:179], v[26:27]
	v_pk_add_f32 v[28:29], v[180:181], v[28:29]
	v_pk_add_f32 v[30:31], v[182:183], v[30:31]
	v_mul_f32_e32 v244, v25, v25
	v_mul_f32_e32 v245, v27, v27
	v_mul_f32_e32 v246, v29, v29
	v_mul_f32_e32 v247, v31, v31
	v_fmac_f32_e32 v244, v24, v24
	v_fmac_f32_e32 v245, v26, v26
	v_fmac_f32_e32 v246, v28, v28
	v_fmac_f32_e32 v247, v30, v30
	v_cvt_pk_bf16_f32 v24, v24, v25
	v_cvt_pk_bf16_f32 v25, v26, v27
	v_cvt_pk_bf16_f32 v26, v28, v29
	v_cvt_pk_bf16_f32 v27, v30, v31
	v_add_f32_e32 v244, v244, v245
	v_add_f32_e32 v245, v246, v247
	v_add_f32_e32 v28, v244, v245
	v_add_u32_e32 v146, 0xa0000, v159
	global_store_dwordx4 v146, v[24:27], s[38:39]
	ds_write_b128 v156, v[12:15]
	ds_write_b128 v156, v[8:11] offset:64
	ds_read_b128 v[8:11], v157
	ds_read_b128 v[12:15], v157 offset:16
	s_waitcnt vmcnt(14) lgkmcnt(4)
; #define PG8_LAS __attribute__((address_space(3)))
; __device__ __forceinline__ unsigned cvt_pk_bf16(float lo, float hi) { unsigned r; asm volatile("v_cvt_pk_bf16_f32 %0, %1, %2" : "=v"(r) : "v"(lo), "v"(hi)); return r; }
;     __device__ __forceinline__ void operator()(const f32x4 (&acc)[2][2][4][2], const Unit& u, int wr, int wc, int fr, int fq) const {
;     ...
;                 for (int bj = 0; bj < 2; ++bj) {
;                     const size_t off = (size_t)row * 2048 + u.pn * BM + wc * 64 + bj * 32 + 8 * p;
;                     f32x4 b0, b1;
;                     if (BASE_F32) { b0 = *(const f32x4*)((const float*)base + off); b1 = *(const f32x4*)((const float*)base + off + 4); }
;                     else { const u32x4 bb = *(const u32x4*)((const bf16_t*)base + off);
;                         b0 = (f32x4){__uint_as_float(bb.x << 16), __uint_as_float(bb.x & 0xffff0000u), __uint_as_float(bb.y << 16), __uint_as_float(bb.y & 0xffff0000u)};
;                         b1 = (f32x4){__uint_as_float(bb.z << 16), __uint_as_float(bb.z & 0xffff0000u), __uint_as_float(bb.w << 16), __uint_as_float(bb.w & 0xffff0000u)}; }
; #pragma unroll
;                     for (int n = 0; n < 2; ++n) *(PG8_LAS f32x4*)(stg + fr * STG_ROW + n * 64 + fq * 16) = acc[ai][bj][m][n];
;                     const f32x4 v0 = *(const PG8_LAS f32x4*)(stg + r * STG_ROW + p * 32) + b0, v1 = *(const PG8_LAS f32x4*)(stg + r * STG_ROW + p * 32 + 16) + b1;
;                     q += ((v0[0] * v0[0] + v0[1] * v0[1]) + (v0[2] * v0[2] + v0[3] * v0[3])) + ((v1[0] * v1[0] + v1[1] * v1[1]) + (v1[2] * v1[2] + v1[3] * v1[3]));
;                     u32x4 w; w.x = cvt_pk_bf16(v0[0], v0[1]); w.y = cvt_pk_bf16(v0[2], v0[3]); w.z = cvt_pk_bf16(v1[0], v1[1]); w.w = cvt_pk_bf16(v1[2], v1[3]);
;                     *(u32x4*)(out + off) = w;
;                 }
;                 q += __shfl_xor(q, 1); q += __shfl_xor(q, 2);
;                 if (p == 0) atomicAdd(ssn + row, (u64)(q * SS_SCALE));
	v_pk_add_f32 v[16:17], v[184:185], v[16:17]
	v_pk_add_f32 v[18:19], v[186:187], v[18:19]
	v_pk_add_f32 v[20:21], v[188:189], v[20:21]
	v_pk_add_f32 v[22:23], v[190:191], v[22:23]
	v_mul_f32_e32 v244, v17, v17
	v_mul_f32_e32 v245, v19, v19
	v_mul_f32_e32 v246, v21, v21
	v_mul_f32_e32 v247, v23, v23
	v_fmac_f32_e32 v244, v16, v16
	v_fmac_f32_e32 v245, v18, v18
	v_fmac_f32_e32 v246, v20, v20
	v_fmac_f32_e32 v247, v22, v22
	v_cvt_pk_bf16_f32 v16, v16, v17
	v_cvt_pk_bf16_f32 v17, v18, v19
	v_cvt_pk_bf16_f32 v18, v20, v21
	v_cvt_pk_bf16_f32 v19, v22, v23
	v_add_f32_e32 v244, v244, v245
	v_add_f32_e32 v245, v246, v247
	v_add_f32_e32 v20, v244, v245
	global_store_dwordx4 v146, v[16:19], s[38:39] offset:64
	v_add_f32_e32 v21, v28, v20
	s_nop 1
	v_add_f32_dpp v22, v21, v21 quad_perm:[1,0,3,2] row_mask:0xf bank_mask:0xf
	s_nop 1
	v_add_f32_dpp v23, v22, v22 quad_perm:[2,3,0,1] row_mask:0xf bank_mask:0xf
	v_mul_f32_e32 v30, 0x49800000, v23
	v_trunc_f32_e32 v30, v30
	v_mul_f32_e32 v31, 0x2f800000, v30
	v_floor_f32_e32 v31, v31
	v_fmac_f32_e32 v30, 0xcf800000, v31
	v_cvt_u32_f32_e32 v30, v30
	v_cvt_u32_f32_e32 v31, v31
	ds_write_b128 v156, v[4:7]
	ds_write_b128 v156, v[0:3] offset:64
	ds_read_b128 v[0:3], v157
	ds_read_b128 v[4:7], v157 offset:16
	s_waitcnt vmcnt(12) lgkmcnt(4)
	v_pk_add_f32 v[8:9], v[192:193], v[8:9]
	v_pk_add_f32 v[10:11], v[194:195], v[10:11]
	v_pk_add_f32 v[12:13], v[196:197], v[12:13]
	v_pk_add_f32 v[14:15], v[198:199], v[14:15]
	v_mul_f32_e32 v244, v9, v9
	v_mul_f32_e32 v245, v11, v11
	v_mul_f32_e32 v246, v13, v13
	v_mul_f32_e32 v247, v15, v15
	v_fmac_f32_e32 v244, v8, v8
	v_fmac_f32_e32 v245, v10, v10
	v_fmac_f32_e32 v246, v12, v12
	v_fmac_f32_e32 v247, v14, v14
	v_cvt_pk_bf16_f32 v8, v8, v9
	v_cvt_pk_bf16_f32 v9, v10, v11
	v_cvt_pk_bf16_f32 v10, v12, v13
	v_cvt_pk_bf16_f32 v11, v14, v15
	v_add_f32_e32 v244, v244, v245
	v_add_f32_e32 v245, v246, v247
	v_add_f32_e32 v12, v244, v245
	v_add_u32_e32 v147, 0xb0000, v159
	global_store_dwordx4 v147, v[8:11], s[38:39]
	s_waitcnt vmcnt(10) lgkmcnt(0)
	v_pk_add_f32 v[0:1], v[200:201], v[0:1]
	v_pk_add_f32 v[2:3], v[202:203], v[2:3]
	v_pk_add_f32 v[4:5], v[204:205], v[4:5]
	v_pk_add_f32 v[6:7], v[206:207], v[6:7]
	v_mul_f32_e32 v244, v1, v1
	v_mul_f32_e32 v245, v3, v3
	v_mul_f32_e32 v246, v5, v5
	v_mul_f32_e32 v247, v7, v7
	v_fmac_f32_e32 v244, v0, v0
	v_fmac_f32_e32 v245, v2, v2
	v_fmac_f32_e32 v246, v4, v4
	v_fmac_f32_e32 v247, v6, v6
	v_cvt_pk_bf16_f32 v0, v0, v1
	v_cvt_pk_bf16_f32 v1, v2, v3
	v_cvt_pk_bf16_f32 v2, v4, v5
	v_cvt_pk_bf16_f32 v3, v6, v7
	v_add_f32_e32 v244, v244, v245
	v_add_f32_e32 v245, v246, v247
	v_add_f32_e32 v4, v244, v245
	global_store_dwordx4 v147, v[0:3], s[38:39] offset:64
	v_add_f32_e32 v5, v12, v4
	s_nop 1
	v_add_f32_dpp v6, v5, v5 quad_perm:[1,0,3,2] row_mask:0xf bank_mask:0xf
	s_nop 1
	v_add_f32_dpp v7, v6, v6 quad_perm:[2,3,0,1] row_mask:0xf bank_mask:0xf
	v_mul_f32_e32 v14, 0x49800000, v7
	v_trunc_f32_e32 v14, v14
	v_mul_f32_e32 v15, 0x2f800000, v14
	v_floor_f32_e32 v15, v15
	v_fmac_f32_e32 v14, 0xcf800000, v15
	v_cvt_u32_f32_e32 v14, v14
	v_cvt_u32_f32_e32 v15, v15
	v_and_b32_e32 v244, 3, v252
	v_lshl_add_u32 v245, v244, 7, v208
	v_cmp_eq_u32_e64 s[100:101], 1, v244
	s_nop 1
	v_cndmask_b32_e64 v126, v126, v110, s[100:101]
	v_cndmask_b32_e64 v127, v127, v111, s[100:101]
	v_cmp_eq_u32_e64 s[100:101], 2, v244
	s_nop 1
	v_cndmask_b32_e64 v126, v126, v94, s[100:101]
	v_cndmask_b32_e64 v127, v127, v95, s[100:101]
	v_cmp_eq_u32_e64 s[100:101], 3, v244
	s_nop 1
	v_cndmask_b32_e64 v126, v126, v78, s[100:101]
	v_cndmask_b32_e64 v127, v127, v79, s[100:101]
	global_atomic_add_x2 v245, v[126:127], s[14:15]
	v_cmp_eq_u32_e64 s[100:101], 1, v244
	s_nop 1
	v_cndmask_b32_e64 v62, v62, v46, s[100:101]
	v_cndmask_b32_e64 v63, v63, v47, s[100:101]
	v_cmp_eq_u32_e64 s[100:101], 2, v244
	s_nop 1
	v_cndmask_b32_e64 v62, v62, v30, s[100:101]
	v_cndmask_b32_e64 v63, v63, v31, s[100:101]
	v_cmp_eq_u32_e64 s[100:101], 3, v244
	s_nop 1
	v_cndmask_b32_e64 v62, v62, v14, s[100:101]
	v_cndmask_b32_e64 v63, v63, v15, s[100:101]
	global_atomic_add_x2 v245, v[62:63], s[14:15] offset:1024
	s_andn2_b64 vcc, exec, s[10:11]
	s_mov_b64 s[10:11], -1
	s_cbranch_vccnz .LBB0_284
	s_andn2_b64 vcc, exec, s[40:41]
	s_cbranch_vccnz .LBB0_283
	s_mov_b32 s98, 1
	s_branch .LBB0_283

; #define PG8_LAS __attribute__((address_space(3)))
; __device__ __forceinline__ unsigned cvt_pk_bf16(float lo, float hi) { unsigned r; asm volatile("v_cvt_pk_bf16_f32 %0, %1, %2" : "=v"(r) : "v"(lo), "v"(hi)); return r; }
;     __device__ __forceinline__ void operator()(const f32x4 (&acc)[2][2][4][2], const Unit& u, int wr, int wc, int fr, int fq) const {
;     ...
;                 for (int bj = 0; bj < 2; ++bj) {
;                     const size_t off = (size_t)row * 2048 + u.pn * BM + wc * 64 + bj * 32 + 8 * p;
;                     f32x4 b0, b1;
;                     if (BASE_F32) { b0 = *(const f32x4*)((const float*)base + off); b1 = *(const f32x4*)((const float*)base + off + 4); }
;                     else { const u32x4 bb = *(const u32x4*)((const bf16_t*)base + off);
;                         b0 = (f32x4){__uint_as_float(bb.x << 16), __uint_as_float(bb.x & 0xffff0000u), __uint_as_float(bb.y << 16), __uint_as_float(bb.y & 0xffff0000u)};
;                         b1 = (f32x4){__uint_as_float(bb.z << 16), __uint_as_float(bb.z & 0xffff0000u), __uint_as_float(bb.w << 16), __uint_as_float(bb.w & 0xffff0000u)}; }
; #pragma unroll
;                     for (int n = 0; n < 2; ++n) *(PG8_LAS f32x4*)(stg + fr * STG_ROW + n * 64 + fq * 16) = acc[ai][bj][m][n];
;                     const f32x4 v0 = *(const PG8_LAS f32x4*)(stg + r * STG_ROW + p * 32) + b0, v1 = *(const PG8_LAS f32x4*)(stg + r * STG_ROW + p * 32 + 16) + b1;
;                     q += ((v0[0] * v0[0] + v0[1] * v0[1]) + (v0[2] * v0[2] + v0[3] * v0[3])) + ((v1[0] * v1[0] + v1[1] * v1[1]) + (v1[2] * v1[2] + v1[3] * v1[3]));
;                     u32x4 w; w.x = cvt_pk_bf16(v0[0], v0[1]); w.y = cvt_pk_bf16(v0[2], v0[3]); w.z = cvt_pk_bf16(v1[0], v1[1]); w.w = cvt_pk_bf16(v1[2], v1[3]);
;                     *(u32x4*)(out + off) = w;
;                 }
;                 q += __shfl_xor(q, 1); q += __shfl_xor(q, 2);
;                 if (p == 0) atomicAdd(ssn + row, (u64)(q * SS_SCALE));
.LBB0_477:
	ds_write_b128 v156, v[124:127]
	ds_write_b128 v156, v[120:123] offset:64
	ds_read_b128 v[120:123], v157
	ds_read_b128 v[124:127], v157 offset:16
	ds_write_b128 v156, v[116:119]
	ds_write_b128 v156, v[112:115] offset:64
	ds_read_b128 v[112:115], v157
	ds_read_b128 v[116:119], v157 offset:16
	s_waitcnt vmcnt(15) lgkmcnt(4)
	v_lshlrev_b32_e32 v236, 16, v160
	v_and_b32_e32 v237, 0xffff0000, v160
	v_lshlrev_b32_e32 v238, 16, v161
	v_and_b32_e32 v239, 0xffff0000, v161
	v_lshlrev_b32_e32 v240, 16, v162
	v_and_b32_e32 v241, 0xffff0000, v162
	v_lshlrev_b32_e32 v242, 16, v163
	v_and_b32_e32 v243, 0xffff0000, v163
	v_pk_add_f32 v[120:121], v[120:121], v[236:237]
	v_pk_add_f32 v[122:123], v[122:123], v[238:239]
	v_pk_add_f32 v[124:125], v[124:125], v[240:241]
	v_pk_add_f32 v[126:127], v[126:127], v[242:243]
	v_mul_f32_e32 v236, v121, v121
	v_mul_f32_e32 v237, v123, v123
	v_mul_f32_e32 v238, v125, v125
	v_mul_f32_e32 v239, v127, v127
	v_fmac_f32_e32 v236, v120, v120
	v_fmac_f32_e32 v237, v122, v122
	v_fmac_f32_e32 v238, v124, v124
	v_fmac_f32_e32 v239, v126, v126
	v_cvt_pk_bf16_f32 v120, v120, v121
	v_cvt_pk_bf16_f32 v121, v122, v123
	v_cvt_pk_bf16_f32 v122, v124, v125
	v_cvt_pk_bf16_f32 v123, v126, v127
	v_add_f32_e32 v236, v236, v237
	v_add_f32_e32 v237, v238, v239
	v_add_f32_e32 v124, v236, v237
	global_store_dwordx4 v159, v[120:123], s[28:29]
	ds_write_b128 v156, v[108:111]
	ds_write_b128 v156, v[104:107] offset:64
	ds_read_b128 v[104:107], v157
	ds_read_b128 v[108:111], v157 offset:16
	s_waitcnt vmcnt(15) lgkmcnt(4)
	v_lshlrev_b32_e32 v236, 16, v164
	v_and_b32_e32 v237, 0xffff0000, v164
	v_lshlrev_b32_e32 v238, 16, v165
	v_and_b32_e32 v239, 0xffff0000, v165
	v_lshlrev_b32_e32 v240, 16, v166
	v_and_b32_e32 v241, 0xffff0000, v166
	v_lshlrev_b32_e32 v242, 16, v167
	v_and_b32_e32 v243, 0xffff0000, v167
	v_pk_add_f32 v[112:113], v[112:113], v[236:237]
	v_pk_add_f32 v[114:115], v[114:115], v[238:239]
	v_pk_add_f32 v[116:117], v[116:117], v[240:241]
	v_pk_add_f32 v[118:119], v[118:119], v[242:243]
	v_mul_f32_e32 v236, v113, v113
	v_mul_f32_e32 v237, v115, v115
	v_mul_f32_e32 v238, v117, v117
	v_mul_f32_e32 v239, v119, v119
	v_fmac_f32_e32 v236, v112, v112
	v_fmac_f32_e32 v237, v114, v114
	v_fmac_f32_e32 v238, v116, v116
	v_fmac_f32_e32 v239, v118, v118
	v_cvt_pk_bf16_f32 v112, v112, v113
	v_cvt_pk_bf16_f32 v113, v114, v115
	v_cvt_pk_bf16_f32 v114, v116, v117
	v_cvt_pk_bf16_f32 v115, v118, v119
	v_add_f32_e32 v236, v236, v237
	v_add_f32_e32 v237, v238, v239
	v_add_f32_e32 v116, v236, v237
	global_store_dwordx4 v159, v[112:115], s[28:29] offset:64
	v_add_f32_e32 v117, v124, v116
	s_nop 1
	v_add_f32_dpp v118, v117, v117 quad_perm:[1,0,3,2] row_mask:0xf bank_mask:0xf
	s_nop 1
	v_add_f32_dpp v119, v118, v118 quad_perm:[2,3,0,1] row_mask:0xf bank_mask:0xf
	v_mul_f32_e32 v126, 0x49800000, v119
	v_trunc_f32_e32 v126, v126
	v_mul_f32_e32 v127, 0x2f800000, v126
	v_floor_f32_e32 v127, v127
	v_fmac_f32_e32 v126, 0xcf800000, v127
	v_cvt_u32_f32_e32 v126, v126
	v_cvt_u32_f32_e32 v127, v127
	ds_write_b128 v156, v[100:103]
	ds_write_b128 v156, v[96:99] offset:64
	ds_read_b128 v[96:99], v157
	ds_read_b128 v[100:103], v157 offset:16
	s_waitcnt vmcnt(15) lgkmcnt(4)
	v_lshlrev_b32_e32 v236, 16, v168
	v_and_b32_e32 v237, 0xffff0000, v168
	v_lshlrev_b32_e32 v238, 16, v169
	v_and_b32_e32 v239, 0xffff0000, v169
	v_lshlrev_b32_e32 v240, 16, v170
	v_and_b32_e32 v241, 0xffff0000, v170
	v_lshlrev_b32_e32 v242, 16, v171
	v_and_b32_e32 v243, 0xffff0000, v171
	v_pk_add_f32 v[104:105], v[104:105], v[236:237]
	v_pk_add_f32 v[106:107], v[106:107], v[238:239]
	v_pk_add_f32 v[108:109], v[108:109], v[240:241]
	v_pk_add_f32 v[110:111], v[110:111], v[242:243]
	v_mul_f32_e32 v236, v105, v105
	v_mul_f32_e32 v237, v107, v107
	v_mul_f32_e32 v238, v109, v109
	v_mul_f32_e32 v239, v111, v111
	v_fmac_f32_e32 v236, v104, v104
	v_fmac_f32_e32 v237, v106, v106
	v_fmac_f32_e32 v238, v108, v108
	v_fmac_f32_e32 v239, v110, v110
	v_cvt_pk_bf16_f32 v104, v104, v105
	v_cvt_pk_bf16_f32 v105, v106, v107
	v_cvt_pk_bf16_f32 v106, v108, v109
	v_cvt_pk_bf16_f32 v107, v110, v111
	v_add_f32_e32 v236, v236, v237
	v_add_f32_e32 v237, v238, v239
	v_add_f32_e32 v108, v236, v237
	v_add_u32_e32 v147, 0x10000, v159
	global_store_dwordx4 v147, v[104:107], s[28:29]
	ds_write_b128 v156, v[92:95]
	ds_write_b128 v156, v[88:91] offset:64
	ds_read_b128 v[88:91], v157
	ds_read_b128 v[92:95], v157 offset:16
	s_waitcnt vmcnt(15) lgkmcnt(4)
	v_lshlrev_b32_e32 v236, 16, v172
	v_and_b32_e32 v237, 0xffff0000, v172
	v_lshlrev_b32_e32 v238, 16, v173
	v_and_b32_e32 v239, 0xffff0000, v173
	v_lshlrev_b32_e32 v240, 16, v174
	v_and_b32_e32 v241, 0xffff0000, v174
	v_lshlrev_b32_e32 v242, 16, v175
	v_and_b32_e32 v243, 0xffff0000, v175
	v_pk_add_f32 v[96:97], v[96:97], v[236:237]
	v_pk_add_f32 v[98:99], v[98:99], v[238:239]
	v_pk_add_f32 v[100:101], v[100:101], v[240:241]
	v_pk_add_f32 v[102:103], v[102:103], v[242:243]
	v_mul_f32_e32 v236, v97, v97
	v_mul_f32_e32 v237, v99, v99
	v_mul_f32_e32 v238, v101, v101
	v_mul_f32_e32 v239, v103, v103
	v_fmac_f32_e32 v236, v96, v96
	v_fmac_f32_e32 v237, v98, v98
	v_fmac_f32_e32 v238, v100, v100
	v_fmac_f32_e32 v239, v102, v102
	v_cvt_pk_bf16_f32 v96, v96, v97
	v_cvt_pk_bf16_f32 v97, v98, v99
	v_cvt_pk_bf16_f32 v98, v100, v101
	v_cvt_pk_bf16_f32 v99, v102, v103
	v_add_f32_e32 v236, v236, v237
	v_add_f32_e32 v237, v238, v239
	v_add_f32_e32 v100, v236, v237
	global_store_dwordx4 v147, v[96:99], s[28:29] offset:64
	v_add_f32_e32 v101, v108, v100
	s_nop 1
	v_add_f32_dpp v102, v101, v101 quad_perm:[1,0,3,2] row_mask:0xf bank_mask:0xf
	s_nop 1
	v_add_f32_dpp v103, v102, v102 quad_perm:[2,3,0,1] row_mask:0xf bank_mask:0xf
	v_mul_f32_e32 v110, 0x49800000, v103
	v_trunc_f32_e32 v110, v110
	v_mul_f32_e32 v111, 0x2f800000, v110
	v_floor_f32_e32 v111, v111
	v_fmac_f32_e32 v110, 0xcf800000, v111
	v_cvt_u32_f32_e32 v110, v110
	v_cvt_u32_f32_e32 v111, v111
	ds_write_b128 v156, v[84:87]
	ds_write_b128 v156, v[80:83] offset:64
	ds_read_b128 v[80:83], v157
	ds_read_b128 v[84:87], v157 offset:16
	s_waitcnt vmcnt(15) lgkmcnt(4)
; #define PG8_LAS __attribute__((address_space(3)))
; __device__ __forceinline__ unsigned cvt_pk_bf16(float lo, float hi) { unsigned r; asm volatile("v_cvt_pk_bf16_f32 %0, %1, %2" : "=v"(r) : "v"(lo), "v"(hi)); return r; }
;     __device__ __forceinline__ void operator()(const f32x4 (&acc)[2][2][4][2], const Unit& u, int wr, int wc, int fr, int fq) const {
;     ...
;                 for (int bj = 0; bj < 2; ++bj) {
;                     const size_t off = (size_t)row * 2048 + u.pn * BM + wc * 64 + bj * 32 + 8 * p;
;                     f32x4 b0, b1;
;                     if (BASE_F32) { b0 = *(const f32x4*)((const float*)base + off); b1 = *(const f32x4*)((const float*)base + off + 4); }
;                     else { const u32x4 bb = *(const u32x4*)((const bf16_t*)base + off);
;                         b0 = (f32x4){__uint_as_float(bb.x << 16), __uint_as_float(bb.x & 0xffff0000u), __uint_as_float(bb.y << 16), __uint_as_float(bb.y & 0xffff0000u)};
;                         b1 = (f32x4){__uint_as_float(bb.z << 16), __uint_as_float(bb.z & 0xffff0000u), __uint_as_float(bb.w << 16), __uint_as_float(bb.w & 0xffff0000u)}; }
; #pragma unroll
;                     for (int n = 0; n < 2; ++n) *(PG8_LAS f32x4*)(stg + fr * STG_ROW + n * 64 + fq * 16) = acc[ai][bj][m][n];
;                     const f32x4 v0 = *(const PG8_LAS f32x4*)(stg + r * STG_ROW + p * 32) + b0, v1 = *(const PG8_LAS f32x4*)(stg + r * STG_ROW + p * 32 + 16) + b1;
;                     q += ((v0[0] * v0[0] + v0[1] * v0[1]) + (v0[2] * v0[2] + v0[3] * v0[3])) + ((v1[0] * v1[0] + v1[1] * v1[1]) + (v1[2] * v1[2] + v1[3] * v1[3]));
;                     u32x4 w; w.x = cvt_pk_bf16(v0[0], v0[1]); w.y = cvt_pk_bf16(v0[2], v0[3]); w.z = cvt_pk_bf16(v1[0], v1[1]); w.w = cvt_pk_bf16(v1[2], v1[3]);
;                     *(u32x4*)(out + off) = w;
;                 }
;                 q += __shfl_xor(q, 1); q += __shfl_xor(q, 2);
;                 if (p == 0) atomicAdd(ssn + row, (u64)(q * SS_SCALE));
	v_lshlrev_b32_e32 v236, 16, v176
	v_and_b32_e32 v237, 0xffff0000, v176
	v_lshlrev_b32_e32 v238, 16, v177
	v_and_b32_e32 v239, 0xffff0000, v177
	v_lshlrev_b32_e32 v240, 16, v178
	v_and_b32_e32 v241, 0xffff0000, v178
	v_lshlrev_b32_e32 v242, 16, v179
	v_and_b32_e32 v243, 0xffff0000, v179
	v_pk_add_f32 v[88:89], v[88:89], v[236:237]
	v_pk_add_f32 v[90:91], v[90:91], v[238:239]
	v_pk_add_f32 v[92:93], v[92:93], v[240:241]
	v_pk_add_f32 v[94:95], v[94:95], v[242:243]
	v_mul_f32_e32 v236, v89, v89
	v_mul_f32_e32 v237, v91, v91
	v_mul_f32_e32 v238, v93, v93
	v_mul_f32_e32 v239, v95, v95
	v_fmac_f32_e32 v236, v88, v88
	v_fmac_f32_e32 v237, v90, v90
	v_fmac_f32_e32 v238, v92, v92
	v_fmac_f32_e32 v239, v94, v94
	v_cvt_pk_bf16_f32 v88, v88, v89
	v_cvt_pk_bf16_f32 v89, v90, v91
	v_cvt_pk_bf16_f32 v90, v92, v93
	v_cvt_pk_bf16_f32 v91, v94, v95
	v_add_f32_e32 v236, v236, v237
	v_add_f32_e32 v237, v238, v239
	v_add_f32_e32 v92, v236, v237
	v_add_u32_e32 v146, 0x20000, v159
	global_store_dwordx4 v146, v[88:91], s[28:29]
	ds_write_b128 v156, v[76:79]
	ds_write_b128 v156, v[72:75] offset:64
	ds_read_b128 v[72:75], v157
	ds_read_b128 v[76:79], v157 offset:16
	s_waitcnt vmcnt(15) lgkmcnt(4)
	v_lshlrev_b32_e32 v236, 16, v180
	v_and_b32_e32 v237, 0xffff0000, v180
	v_lshlrev_b32_e32 v238, 16, v181
	v_and_b32_e32 v239, 0xffff0000, v181
	v_lshlrev_b32_e32 v240, 16, v182
	v_and_b32_e32 v241, 0xffff0000, v182
	v_lshlrev_b32_e32 v242, 16, v183
	v_and_b32_e32 v243, 0xffff0000, v183
	v_pk_add_f32 v[80:81], v[80:81], v[236:237]
	v_pk_add_f32 v[82:83], v[82:83], v[238:239]
	v_pk_add_f32 v[84:85], v[84:85], v[240:241]
	v_pk_add_f32 v[86:87], v[86:87], v[242:243]
	v_mul_f32_e32 v236, v81, v81
	v_mul_f32_e32 v237, v83, v83
	v_mul_f32_e32 v238, v85, v85
	v_mul_f32_e32 v239, v87, v87
	v_fmac_f32_e32 v236, v80, v80
	v_fmac_f32_e32 v237, v82, v82
	v_fmac_f32_e32 v238, v84, v84
	v_fmac_f32_e32 v239, v86, v86
	v_cvt_pk_bf16_f32 v80, v80, v81
	v_cvt_pk_bf16_f32 v81, v82, v83
	v_cvt_pk_bf16_f32 v82, v84, v85
	v_cvt_pk_bf16_f32 v83, v86, v87
	v_add_f32_e32 v236, v236, v237
	v_add_f32_e32 v237, v238, v239
	v_add_f32_e32 v84, v236, v237
	global_store_dwordx4 v146, v[80:83], s[28:29] offset:64
	v_add_f32_e32 v85, v92, v84
	s_nop 1
	v_add_f32_dpp v86, v85, v85 quad_perm:[1,0,3,2] row_mask:0xf bank_mask:0xf
	s_nop 1
	v_add_f32_dpp v87, v86, v86 quad_perm:[2,3,0,1] row_mask:0xf bank_mask:0xf
	v_mul_f32_e32 v94, 0x49800000, v87
	v_trunc_f32_e32 v94, v94
	v_mul_f32_e32 v95, 0x2f800000, v94
	v_floor_f32_e32 v95, v95
	v_fmac_f32_e32 v94, 0xcf800000, v95
	v_cvt_u32_f32_e32 v94, v94
	v_cvt_u32_f32_e32 v95, v95
	ds_write_b128 v156, v[68:71]
	ds_write_b128 v156, v[64:67] offset:64
	ds_read_b128 v[64:67], v157
	ds_read_b128 v[68:71], v157 offset:16
	s_waitcnt vmcnt(15) lgkmcnt(4)
	v_lshlrev_b32_e32 v236, 16, v184
	v_and_b32_e32 v237, 0xffff0000, v184
	v_lshlrev_b32_e32 v238, 16, v185
	v_and_b32_e32 v239, 0xffff0000, v185
	v_lshlrev_b32_e32 v240, 16, v186
	v_and_b32_e32 v241, 0xffff0000, v186
	v_lshlrev_b32_e32 v242, 16, v187
	v_and_b32_e32 v243, 0xffff0000, v187
	v_pk_add_f32 v[72:73], v[72:73], v[236:237]
	v_pk_add_f32 v[74:75], v[74:75], v[238:239]
	v_pk_add_f32 v[76:77], v[76:77], v[240:241]
	v_pk_add_f32 v[78:79], v[78:79], v[242:243]
	v_mul_f32_e32 v236, v73, v73
	v_mul_f32_e32 v237, v75, v75
	v_mul_f32_e32 v238, v77, v77
	v_mul_f32_e32 v239, v79, v79
	v_fmac_f32_e32 v236, v72, v72
	v_fmac_f32_e32 v237, v74, v74
	v_fmac_f32_e32 v238, v76, v76
	v_fmac_f32_e32 v239, v78, v78
	v_cvt_pk_bf16_f32 v72, v72, v73
	v_cvt_pk_bf16_f32 v73, v74, v75
	v_cvt_pk_bf16_f32 v74, v76, v77
	v_cvt_pk_bf16_f32 v75, v78, v79
	v_add_f32_e32 v236, v236, v237
	v_add_f32_e32 v237, v238, v239
	v_add_f32_e32 v76, v236, v237
	v_add_u32_e32 v147, 0x30000, v159
	global_store_dwordx4 v147, v[72:75], s[28:29]
	ds_write_b128 v156, v[60:63]
	ds_write_b128 v156, v[56:59] offset:64
	ds_read_b128 v[56:59], v157
	ds_read_b128 v[60:63], v157 offset:16
	s_waitcnt vmcnt(15) lgkmcnt(4)
	v_lshlrev_b32_e32 v236, 16, v188
	v_and_b32_e32 v237, 0xffff0000, v188
	v_lshlrev_b32_e32 v238, 16, v189
	v_and_b32_e32 v239, 0xffff0000, v189
	v_lshlrev_b32_e32 v240, 16, v190
	v_and_b32_e32 v241, 0xffff0000, v190
	v_lshlrev_b32_e32 v242, 16, v191
	v_and_b32_e32 v243, 0xffff0000, v191
	v_pk_add_f32 v[64:65], v[64:65], v[236:237]
	v_pk_add_f32 v[66:67], v[66:67], v[238:239]
	v_pk_add_f32 v[68:69], v[68:69], v[240:241]
	v_pk_add_f32 v[70:71], v[70:71], v[242:243]
	v_mul_f32_e32 v236, v65, v65
	v_mul_f32_e32 v237, v67, v67
	v_mul_f32_e32 v238, v69, v69
	v_mul_f32_e32 v239, v71, v71
	v_fmac_f32_e32 v236, v64, v64
	v_fmac_f32_e32 v237, v66, v66
	v_fmac_f32_e32 v238, v68, v68
	v_fmac_f32_e32 v239, v70, v70
	v_cvt_pk_bf16_f32 v64, v64, v65
	v_cvt_pk_bf16_f32 v65, v66, v67
	v_cvt_pk_bf16_f32 v66, v68, v69
	v_cvt_pk_bf16_f32 v67, v70, v71
	v_add_f32_e32 v236, v236, v237
	v_add_f32_e32 v237, v238, v239
	v_add_f32_e32 v68, v236, v237
	global_store_dwordx4 v147, v[64:67], s[28:29] offset:64
	v_add_f32_e32 v69, v76, v68
	s_nop 1
	v_add_f32_dpp v70, v69, v69 quad_perm:[1,0,3,2] row_mask:0xf bank_mask:0xf
	s_nop 1
	v_add_f32_dpp v71, v70, v70 quad_perm:[2,3,0,1] row_mask:0xf bank_mask:0xf
	v_mul_f32_e32 v78, 0x49800000, v71
	v_trunc_f32_e32 v78, v78
	v_mul_f32_e32 v79, 0x2f800000, v78
	v_floor_f32_e32 v79, v79
	v_fmac_f32_e32 v78, 0xcf800000, v79
	v_cvt_u32_f32_e32 v78, v78
	v_cvt_u32_f32_e32 v79, v79
	ds_write_b128 v156, v[52:55]
	ds_write_b128 v156, v[48:51] offset:64
	ds_read_b128 v[48:51], v157
	ds_read_b128 v[52:55], v157 offset:16
	s_waitcnt vmcnt(15) lgkmcnt(4)
; #define PG8_LAS __attribute__((address_space(3)))
; __device__ __forceinline__ unsigned cvt_pk_bf16(float lo, float hi) { unsigned r; asm volatile("v_cvt_pk_bf16_f32 %0, %1, %2" : "=v"(r) : "v"(lo), "v"(hi)); return r; }
;     __device__ __forceinline__ void operator()(const f32x4 (&acc)[2][2][4][2], const Unit& u, int wr, int wc, int fr, int fq) const {
;     ...
;                 for (int bj = 0; bj < 2; ++bj) {
;                     const size_t off = (size_t)row * 2048 + u.pn * BM + wc * 64 + bj * 32 + 8 * p;
;                     f32x4 b0, b1;
;                     if (BASE_F32) { b0 = *(const f32x4*)((const float*)base + off); b1 = *(const f32x4*)((const float*)base + off + 4); }
;                     else { const u32x4 bb = *(const u32x4*)((const bf16_t*)base + off);
;                         b0 = (f32x4){__uint_as_float(bb.x << 16), __uint_as_float(bb.x & 0xffff0000u), __uint_as_float(bb.y << 16), __uint_as_float(bb.y & 0xffff0000u)};
;                         b1 = (f32x4){__uint_as_float(bb.z << 16), __uint_as_float(bb.z & 0xffff0000u), __uint_as_float(bb.w << 16), __uint_as_float(bb.w & 0xffff0000u)}; }
; #pragma unroll
;                     for (int n = 0; n < 2; ++n) *(PG8_LAS f32x4*)(stg + fr * STG_ROW + n * 64 + fq * 16) = acc[ai][bj][m][n];
;                     const f32x4 v0 = *(const PG8_LAS f32x4*)(stg + r * STG_ROW + p * 32) + b0, v1 = *(const PG8_LAS f32x4*)(stg + r * STG_ROW + p * 32 + 16) + b1;
;                     q += ((v0[0] * v0[0] + v0[1] * v0[1]) + (v0[2] * v0[2] + v0[3] * v0[3])) + ((v1[0] * v1[0] + v1[1] * v1[1]) + (v1[2] * v1[2] + v1[3] * v1[3]));
;                     u32x4 w; w.x = cvt_pk_bf16(v0[0], v0[1]); w.y = cvt_pk_bf16(v0[2], v0[3]); w.z = cvt_pk_bf16(v1[0], v1[1]); w.w = cvt_pk_bf16(v1[2], v1[3]);
;                     *(u32x4*)(out + off) = w;
;                 }
;                 q += __shfl_xor(q, 1); q += __shfl_xor(q, 2);
;                 if (p == 0) atomicAdd(ssn + row, (u64)(q * SS_SCALE));
	v_lshlrev_b32_e32 v236, 16, v192
	v_and_b32_e32 v237, 0xffff0000, v192
	v_lshlrev_b32_e32 v238, 16, v193
	v_and_b32_e32 v239, 0xffff0000, v193
	v_lshlrev_b32_e32 v240, 16, v194
	v_and_b32_e32 v241, 0xffff0000, v194
	v_lshlrev_b32_e32 v242, 16, v195
	v_and_b32_e32 v243, 0xffff0000, v195
	v_pk_add_f32 v[56:57], v[56:57], v[236:237]
	v_pk_add_f32 v[58:59], v[58:59], v[238:239]
	v_pk_add_f32 v[60:61], v[60:61], v[240:241]
	v_pk_add_f32 v[62:63], v[62:63], v[242:243]
	v_mul_f32_e32 v236, v57, v57
	v_mul_f32_e32 v237, v59, v59
	v_mul_f32_e32 v238, v61, v61
	v_mul_f32_e32 v239, v63, v63
	v_fmac_f32_e32 v236, v56, v56
	v_fmac_f32_e32 v237, v58, v58
	v_fmac_f32_e32 v238, v60, v60
	v_fmac_f32_e32 v239, v62, v62
	v_cvt_pk_bf16_f32 v56, v56, v57
	v_cvt_pk_bf16_f32 v57, v58, v59
	v_cvt_pk_bf16_f32 v58, v60, v61
	v_cvt_pk_bf16_f32 v59, v62, v63
	v_add_f32_e32 v236, v236, v237
	v_add_f32_e32 v237, v238, v239
	v_add_f32_e32 v60, v236, v237
	v_add_u32_e32 v146, 0x80000, v159
	global_store_dwordx4 v146, v[56:59], s[28:29]
	ds_write_b128 v156, v[44:47]
	ds_write_b128 v156, v[40:43] offset:64
	ds_read_b128 v[40:43], v157
	ds_read_b128 v[44:47], v157 offset:16
	s_waitcnt vmcnt(15) lgkmcnt(4)
	v_lshlrev_b32_e32 v236, 16, v196
	v_and_b32_e32 v237, 0xffff0000, v196
	v_lshlrev_b32_e32 v238, 16, v197
	v_and_b32_e32 v239, 0xffff0000, v197
	v_lshlrev_b32_e32 v240, 16, v198
	v_and_b32_e32 v241, 0xffff0000, v198
	v_lshlrev_b32_e32 v242, 16, v199
	v_and_b32_e32 v243, 0xffff0000, v199
	v_pk_add_f32 v[48:49], v[48:49], v[236:237]
	v_pk_add_f32 v[50:51], v[50:51], v[238:239]
	v_pk_add_f32 v[52:53], v[52:53], v[240:241]
	v_pk_add_f32 v[54:55], v[54:55], v[242:243]
	v_mul_f32_e32 v236, v49, v49
	v_mul_f32_e32 v237, v51, v51
	v_mul_f32_e32 v238, v53, v53
	v_mul_f32_e32 v239, v55, v55
	v_fmac_f32_e32 v236, v48, v48
	v_fmac_f32_e32 v237, v50, v50
	v_fmac_f32_e32 v238, v52, v52
	v_fmac_f32_e32 v239, v54, v54
	v_cvt_pk_bf16_f32 v48, v48, v49
	v_cvt_pk_bf16_f32 v49, v50, v51
	v_cvt_pk_bf16_f32 v50, v52, v53
	v_cvt_pk_bf16_f32 v51, v54, v55
	v_add_f32_e32 v236, v236, v237
	v_add_f32_e32 v237, v238, v239
	v_add_f32_e32 v52, v236, v237
	global_store_dwordx4 v146, v[48:51], s[28:29] offset:64
	v_add_f32_e32 v53, v60, v52
	s_nop 1
	v_add_f32_dpp v54, v53, v53 quad_perm:[1,0,3,2] row_mask:0xf bank_mask:0xf
	s_nop 1
	v_add_f32_dpp v55, v54, v54 quad_perm:[2,3,0,1] row_mask:0xf bank_mask:0xf
	v_mul_f32_e32 v62, 0x49800000, v55
	v_trunc_f32_e32 v62, v62
	v_mul_f32_e32 v63, 0x2f800000, v62
	v_floor_f32_e32 v63, v63
	v_fmac_f32_e32 v62, 0xcf800000, v63
	v_cvt_u32_f32_e32 v62, v62
	v_cvt_u32_f32_e32 v63, v63
	ds_write_b128 v156, v[36:39]
	ds_write_b128 v156, v[32:35] offset:64
	ds_read_b128 v[32:35], v157
	ds_read_b128 v[36:39], v157 offset:16
	s_waitcnt vmcnt(15) lgkmcnt(4)
	v_lshlrev_b32_e32 v236, 16, v200
	v_and_b32_e32 v237, 0xffff0000, v200
	v_lshlrev_b32_e32 v238, 16, v201
	v_and_b32_e32 v239, 0xffff0000, v201
	v_lshlrev_b32_e32 v240, 16, v202
	v_and_b32_e32 v241, 0xffff0000, v202
	v_lshlrev_b32_e32 v242, 16, v203
	v_and_b32_e32 v243, 0xffff0000, v203
	v_pk_add_f32 v[40:41], v[40:41], v[236:237]
	v_pk_add_f32 v[42:43], v[42:43], v[238:239]
	v_pk_add_f32 v[44:45], v[44:45], v[240:241]
	v_pk_add_f32 v[46:47], v[46:47], v[242:243]
	v_mul_f32_e32 v236, v41, v41
	v_mul_f32_e32 v237, v43, v43
	v_mul_f32_e32 v238, v45, v45
	v_mul_f32_e32 v239, v47, v47
	v_fmac_f32_e32 v236, v40, v40
	v_fmac_f32_e32 v237, v42, v42
	v_fmac_f32_e32 v238, v44, v44
	v_fmac_f32_e32 v239, v46, v46
	v_cvt_pk_bf16_f32 v40, v40, v41
	v_cvt_pk_bf16_f32 v41, v42, v43
	v_cvt_pk_bf16_f32 v42, v44, v45
	v_cvt_pk_bf16_f32 v43, v46, v47
	v_add_f32_e32 v236, v236, v237
	v_add_f32_e32 v237, v238, v239
	v_add_f32_e32 v44, v236, v237
	v_add_u32_e32 v147, 0x90000, v159
	global_store_dwordx4 v147, v[40:43], s[28:29]
	ds_write_b128 v156, v[28:31]
	ds_write_b128 v156, v[24:27] offset:64
	ds_read_b128 v[24:27], v157
	ds_read_b128 v[28:31], v157 offset:16
	s_waitcnt vmcnt(15) lgkmcnt(4)
	v_lshlrev_b32_e32 v236, 16, v204
	v_and_b32_e32 v237, 0xffff0000, v204
	v_lshlrev_b32_e32 v238, 16, v205
	v_and_b32_e32 v239, 0xffff0000, v205
	v_lshlrev_b32_e32 v240, 16, v206
	v_and_b32_e32 v241, 0xffff0000, v206
	v_lshlrev_b32_e32 v242, 16, v207
	v_and_b32_e32 v243, 0xffff0000, v207
	v_pk_add_f32 v[32:33], v[32:33], v[236:237]
	v_pk_add_f32 v[34:35], v[34:35], v[238:239]
	v_pk_add_f32 v[36:37], v[36:37], v[240:241]
	v_pk_add_f32 v[38:39], v[38:39], v[242:243]
	v_mul_f32_e32 v236, v33, v33
	v_mul_f32_e32 v237, v35, v35
	v_mul_f32_e32 v238, v37, v37
	v_mul_f32_e32 v239, v39, v39
	v_fmac_f32_e32 v236, v32, v32
	v_fmac_f32_e32 v237, v34, v34
	v_fmac_f32_e32 v238, v36, v36
	v_fmac_f32_e32 v239, v38, v38
	v_cvt_pk_bf16_f32 v32, v32, v33
	v_cvt_pk_bf16_f32 v33, v34, v35
	v_cvt_pk_bf16_f32 v34, v36, v37
	v_cvt_pk_bf16_f32 v35, v38, v39
	v_add_f32_e32 v236, v236, v237
	v_add_f32_e32 v237, v238, v239
	v_add_f32_e32 v36, v236, v237
	global_store_dwordx4 v147, v[32:35], s[28:29] offset:64
	v_add_f32_e32 v37, v44, v36
	s_nop 1
	v_add_f32_dpp v38, v37, v37 quad_perm:[1,0,3,2] row_mask:0xf bank_mask:0xf
	s_nop 1
	v_add_f32_dpp v39, v38, v38 quad_perm:[2,3,0,1] row_mask:0xf bank_mask:0xf
	v_mul_f32_e32 v46, 0x49800000, v39
	v_trunc_f32_e32 v46, v46
	v_mul_f32_e32 v47, 0x2f800000, v46
	v_floor_f32_e32 v47, v47
	v_fmac_f32_e32 v46, 0xcf800000, v47
	v_cvt_u32_f32_e32 v46, v46
	v_cvt_u32_f32_e32 v47, v47
	ds_write_b128 v156, v[20:23]
	ds_write_b128 v156, v[16:19] offset:64
	ds_read_b128 v[16:19], v157
	ds_read_b128 v[20:23], v157 offset:16
	s_waitcnt vmcnt(15) lgkmcnt(4)
; #define PG8_LAS __attribute__((address_space(3)))
; __device__ __forceinline__ unsigned cvt_pk_bf16(float lo, float hi) { unsigned r; asm volatile("v_cvt_pk_bf16_f32 %0, %1, %2" : "=v"(r) : "v"(lo), "v"(hi)); return r; }
;     __device__ __forceinline__ void operator()(const f32x4 (&acc)[2][2][4][2], const Unit& u, int wr, int wc, int fr, int fq) const {
;     ...
;                 for (int bj = 0; bj < 2; ++bj) {
;                     const size_t off = (size_t)row * 2048 + u.pn * BM + wc * 64 + bj * 32 + 8 * p;
;                     f32x4 b0, b1;
;                     if (BASE_F32) { b0 = *(const f32x4*)((const float*)base + off); b1 = *(const f32x4*)((const float*)base + off + 4); }
;                     else { const u32x4 bb = *(const u32x4*)((const bf16_t*)base + off);
;                         b0 = (f32x4){__uint_as_float(bb.x << 16), __uint_as_float(bb.x & 0xffff0000u), __uint_as_float(bb.y << 16), __uint_as_float(bb.y & 0xffff0000u)};
;                         b1 = (f32x4){__uint_as_float(bb.z << 16), __uint_as_float(bb.z & 0xffff0000u), __uint_as_float(bb.w << 16), __uint_as_float(bb.w & 0xffff0000u)}; }
; #pragma unroll
;                     for (int n = 0; n < 2; ++n) *(PG8_LAS f32x4*)(stg + fr * STG_ROW + n * 64 + fq * 16) = acc[ai][bj][m][n];
;                     const f32x4 v0 = *(const PG8_LAS f32x4*)(stg + r * STG_ROW + p * 32) + b0, v1 = *(const PG8_LAS f32x4*)(stg + r * STG_ROW + p * 32 + 16) + b1;
;                     q += ((v0[0] * v0[0] + v0[1] * v0[1]) + (v0[2] * v0[2] + v0[3] * v0[3])) + ((v1[0] * v1[0] + v1[1] * v1[1]) + (v1[2] * v1[2] + v1[3] * v1[3]));
;                     u32x4 w; w.x = cvt_pk_bf16(v0[0], v0[1]); w.y = cvt_pk_bf16(v0[2], v0[3]); w.z = cvt_pk_bf16(v1[0], v1[1]); w.w = cvt_pk_bf16(v1[2], v1[3]);
;                     *(u32x4*)(out + off) = w;
;                 }
;                 q += __shfl_xor(q, 1); q += __shfl_xor(q, 2);
;                 if (p == 0) atomicAdd(ssn + row, (u64)(q * SS_SCALE));
	v_lshlrev_b32_e32 v236, 16, v212
	v_and_b32_e32 v237, 0xffff0000, v212
	v_lshlrev_b32_e32 v238, 16, v213
	v_and_b32_e32 v239, 0xffff0000, v213
	v_lshlrev_b32_e32 v240, 16, v214
	v_and_b32_e32 v241, 0xffff0000, v214
	v_lshlrev_b32_e32 v242, 16, v215
	v_and_b32_e32 v243, 0xffff0000, v215
	v_pk_add_f32 v[24:25], v[24:25], v[236:237]
	v_pk_add_f32 v[26:27], v[26:27], v[238:239]
	v_pk_add_f32 v[28:29], v[28:29], v[240:241]
	v_pk_add_f32 v[30:31], v[30:31], v[242:243]
	v_mul_f32_e32 v236, v25, v25
	v_mul_f32_e32 v237, v27, v27
	v_mul_f32_e32 v238, v29, v29
	v_mul_f32_e32 v239, v31, v31
	v_fmac_f32_e32 v236, v24, v24
	v_fmac_f32_e32 v237, v26, v26
	v_fmac_f32_e32 v238, v28, v28
	v_fmac_f32_e32 v239, v30, v30
	v_cvt_pk_bf16_f32 v24, v24, v25
	v_cvt_pk_bf16_f32 v25, v26, v27
	v_cvt_pk_bf16_f32 v26, v28, v29
	v_cvt_pk_bf16_f32 v27, v30, v31
	v_add_f32_e32 v236, v236, v237
	v_add_f32_e32 v237, v238, v239
	v_add_f32_e32 v28, v236, v237
	v_add_u32_e32 v146, 0xa0000, v159
	global_store_dwordx4 v146, v[24:27], s[28:29]
	ds_write_b128 v156, v[12:15]
	ds_write_b128 v156, v[8:11] offset:64
	ds_read_b128 v[8:11], v157
	ds_read_b128 v[12:15], v157 offset:16
	s_waitcnt vmcnt(15) lgkmcnt(4)
	v_lshlrev_b32_e32 v236, 16, v216
	v_and_b32_e32 v237, 0xffff0000, v216
	v_lshlrev_b32_e32 v238, 16, v217
	v_and_b32_e32 v239, 0xffff0000, v217
	v_lshlrev_b32_e32 v240, 16, v218
	v_and_b32_e32 v241, 0xffff0000, v218
	v_lshlrev_b32_e32 v242, 16, v219
	v_and_b32_e32 v243, 0xffff0000, v219
	v_pk_add_f32 v[16:17], v[16:17], v[236:237]
	v_pk_add_f32 v[18:19], v[18:19], v[238:239]
	v_pk_add_f32 v[20:21], v[20:21], v[240:241]
	v_pk_add_f32 v[22:23], v[22:23], v[242:243]
	v_mul_f32_e32 v236, v17, v17
	v_mul_f32_e32 v237, v19, v19
	v_mul_f32_e32 v238, v21, v21
	v_mul_f32_e32 v239, v23, v23
	v_fmac_f32_e32 v236, v16, v16
	v_fmac_f32_e32 v237, v18, v18
	v_fmac_f32_e32 v238, v20, v20
	v_fmac_f32_e32 v239, v22, v22
	v_cvt_pk_bf16_f32 v16, v16, v17
	v_cvt_pk_bf16_f32 v17, v18, v19
	v_cvt_pk_bf16_f32 v18, v20, v21
	v_cvt_pk_bf16_f32 v19, v22, v23
	v_add_f32_e32 v236, v236, v237
	v_add_f32_e32 v237, v238, v239
	v_add_f32_e32 v20, v236, v237
	global_store_dwordx4 v146, v[16:19], s[28:29] offset:64
	v_add_f32_e32 v21, v28, v20
	s_nop 1
	v_add_f32_dpp v22, v21, v21 quad_perm:[1,0,3,2] row_mask:0xf bank_mask:0xf
	s_nop 1
	v_add_f32_dpp v23, v22, v22 quad_perm:[2,3,0,1] row_mask:0xf bank_mask:0xf
	v_mul_f32_e32 v30, 0x49800000, v23
	v_trunc_f32_e32 v30, v30
	v_mul_f32_e32 v31, 0x2f800000, v30
	v_floor_f32_e32 v31, v31
	v_fmac_f32_e32 v30, 0xcf800000, v31
	v_cvt_u32_f32_e32 v30, v30
	v_cvt_u32_f32_e32 v31, v31
	ds_write_b128 v156, v[4:7]
	ds_write_b128 v156, v[0:3] offset:64
	ds_read_b128 v[0:3], v157
	ds_read_b128 v[4:7], v157 offset:16
	s_waitcnt vmcnt(15) lgkmcnt(4)
	v_lshlrev_b32_e32 v236, 16, v220
	v_and_b32_e32 v237, 0xffff0000, v220
	v_lshlrev_b32_e32 v238, 16, v221
	v_and_b32_e32 v239, 0xffff0000, v221
	v_lshlrev_b32_e32 v240, 16, v222
	v_and_b32_e32 v241, 0xffff0000, v222
	v_lshlrev_b32_e32 v242, 16, v223
	v_and_b32_e32 v243, 0xffff0000, v223
	v_pk_add_f32 v[8:9], v[8:9], v[236:237]
	v_pk_add_f32 v[10:11], v[10:11], v[238:239]
	v_pk_add_f32 v[12:13], v[12:13], v[240:241]
	v_pk_add_f32 v[14:15], v[14:15], v[242:243]
	v_mul_f32_e32 v236, v9, v9
	v_mul_f32_e32 v237, v11, v11
	v_mul_f32_e32 v238, v13, v13
	v_mul_f32_e32 v239, v15, v15
	v_fmac_f32_e32 v236, v8, v8
	v_fmac_f32_e32 v237, v10, v10
	v_fmac_f32_e32 v238, v12, v12
	v_fmac_f32_e32 v239, v14, v14
	v_cvt_pk_bf16_f32 v8, v8, v9
	v_cvt_pk_bf16_f32 v9, v10, v11
	v_cvt_pk_bf16_f32 v10, v12, v13
	v_cvt_pk_bf16_f32 v11, v14, v15
	v_add_f32_e32 v236, v236, v237
	v_add_f32_e32 v237, v238, v239
	v_add_f32_e32 v12, v236, v237
	v_add_u32_e32 v147, 0xb0000, v159
	global_store_dwordx4 v147, v[8:11], s[28:29]
	s_waitcnt vmcnt(15) lgkmcnt(0)
	v_lshlrev_b32_e32 v236, 16, v224
	v_and_b32_e32 v237, 0xffff0000, v224
	v_lshlrev_b32_e32 v238, 16, v225
	v_and_b32_e32 v239, 0xffff0000, v225
	v_lshlrev_b32_e32 v240, 16, v226
	v_and_b32_e32 v241, 0xffff0000, v226
	v_lshlrev_b32_e32 v242, 16, v227
	v_and_b32_e32 v243, 0xffff0000, v227
	v_pk_add_f32 v[0:1], v[0:1], v[236:237]
	v_pk_add_f32 v[2:3], v[2:3], v[238:239]
	v_pk_add_f32 v[4:5], v[4:5], v[240:241]
	v_pk_add_f32 v[6:7], v[6:7], v[242:243]
	v_mul_f32_e32 v236, v1, v1
	v_mul_f32_e32 v237, v3, v3
	v_mul_f32_e32 v238, v5, v5
	v_mul_f32_e32 v239, v7, v7
	v_fmac_f32_e32 v236, v0, v0
	v_fmac_f32_e32 v237, v2, v2
	v_fmac_f32_e32 v238, v4, v4
	v_fmac_f32_e32 v239, v6, v6
	v_cvt_pk_bf16_f32 v0, v0, v1
	v_cvt_pk_bf16_f32 v1, v2, v3
	v_cvt_pk_bf16_f32 v2, v4, v5
	v_cvt_pk_bf16_f32 v3, v6, v7
	v_add_f32_e32 v236, v236, v237
	v_add_f32_e32 v237, v238, v239
	v_add_f32_e32 v4, v236, v237
	global_store_dwordx4 v147, v[0:3], s[28:29] offset:64
	v_add_f32_e32 v5, v12, v4
	s_nop 1
	v_add_f32_dpp v6, v5, v5 quad_perm:[1,0,3,2] row_mask:0xf bank_mask:0xf
	s_nop 1
	v_add_f32_dpp v7, v6, v6 quad_perm:[2,3,0,1] row_mask:0xf bank_mask:0xf
	v_mul_f32_e32 v14, 0x49800000, v7
	v_trunc_f32_e32 v14, v14
	v_mul_f32_e32 v15, 0x2f800000, v14
	v_floor_f32_e32 v15, v15
	v_fmac_f32_e32 v14, 0xcf800000, v15
	v_cvt_u32_f32_e32 v14, v14
	v_cvt_u32_f32_e32 v15, v15
	v_and_b32_e32 v236, 3, v252
	v_lshl_add_u32 v237, v236, 7, v208
	v_cmp_eq_u32_e64 s[100:101], 1, v236
	s_nop 1
	v_cndmask_b32_e64 v126, v126, v110, s[100:101]
	v_cndmask_b32_e64 v127, v127, v111, s[100:101]
	v_cmp_eq_u32_e64 s[100:101], 2, v236
	s_nop 1
	v_cndmask_b32_e64 v126, v126, v94, s[100:101]
	v_cndmask_b32_e64 v127, v127, v95, s[100:101]
	v_cmp_eq_u32_e64 s[100:101], 3, v236
	s_nop 1
	v_cndmask_b32_e64 v126, v126, v78, s[100:101]
	v_cndmask_b32_e64 v127, v127, v79, s[100:101]
	global_atomic_add_x2 v237, v[126:127], s[44:45]
	v_cmp_eq_u32_e64 s[100:101], 1, v236
	s_nop 1
	v_cndmask_b32_e64 v62, v62, v46, s[100:101]
	v_cndmask_b32_e64 v63, v63, v47, s[100:101]
	v_cmp_eq_u32_e64 s[100:101], 2, v236
	s_nop 1
	v_cndmask_b32_e64 v62, v62, v30, s[100:101]
	v_cndmask_b32_e64 v63, v63, v31, s[100:101]
	v_cmp_eq_u32_e64 s[100:101], 3, v236
	s_nop 1
	v_cndmask_b32_e64 v62, v62, v14, s[100:101]
	v_cndmask_b32_e64 v63, v63, v15, s[100:101]
	global_atomic_add_x2 v237, v[62:63], s[44:45] offset:1024
	s_and_b64 vcc, exec, s[10:11]
	s_mov_b64 s[10:11], -1
	s_cbranch_vccnz .LBB0_464
	s_andn2_b64 vcc, exec, s[14:15]
	s_cbranch_vccnz .LBB0_463
	s_mov_b32 s98, 1
	s_branch .LBB0_463

; #define PG8_LAS __attribute__((address_space(3)))
; __device__ __forceinline__ unsigned cvt_pk_bf16(float lo, float hi) { unsigned r; asm volatile("v_cvt_pk_bf16_f32 %0, %1, %2" : "=v"(r) : "v"(lo), "v"(hi)); return r; }
;     __device__ __forceinline__ void operator()(const f32x4 (&acc)[2][2][4][2], const Unit& u, int wr, int wc, int fr, int fq) const {
;     ...
;                 for (int bj = 0; bj < 2; ++bj) {
;                     const size_t off = (size_t)row * 2048 + u.pn * BM + wc * 64 + bj * 32 + 8 * p;
;                     f32x4 b0, b1;
;                     if (BASE_F32) { b0 = *(const f32x4*)((const float*)base + off); b1 = *(const f32x4*)((const float*)base + off + 4); }
;                     else { const u32x4 bb = *(const u32x4*)((const bf16_t*)base + off);
;                         b0 = (f32x4){__uint_as_float(bb.x << 16), __uint_as_float(bb.x & 0xffff0000u), __uint_as_float(bb.y << 16), __uint_as_float(bb.y & 0xffff0000u)};
;                         b1 = (f32x4){__uint_as_float(bb.z << 16), __uint_as_float(bb.z & 0xffff0000u), __uint_as_float(bb.w << 16), __uint_as_float(bb.w & 0xffff0000u)}; }
; #pragma unroll
;                     for (int n = 0; n < 2; ++n) *(PG8_LAS f32x4*)(stg + fr * STG_ROW + n * 64 + fq * 16) = acc[ai][bj][m][n];
;                     const f32x4 v0 = *(const PG8_LAS f32x4*)(stg + r * STG_ROW + p * 32) + b0, v1 = *(const PG8_LAS f32x4*)(stg + r * STG_ROW + p * 32 + 16) + b1;
;                     q += ((v0[0] * v0[0] + v0[1] * v0[1]) + (v0[2] * v0[2] + v0[3] * v0[3])) + ((v1[0] * v1[0] + v1[1] * v1[1]) + (v1[2] * v1[2] + v1[3] * v1[3]));
;                     u32x4 w; w.x = cvt_pk_bf16(v0[0], v0[1]); w.y = cvt_pk_bf16(v0[2], v0[3]); w.z = cvt_pk_bf16(v1[0], v1[1]); w.w = cvt_pk_bf16(v1[2], v1[3]);
;                     *(u32x4*)(out + off) = w;
;                 }
;                 q += __shfl_xor(q, 1); q += __shfl_xor(q, 2);
;                 if (p == 0) atomicAdd(ssn + row, (u64)(q * SS_SCALE));
.LBB0_770:
	ds_write_b128 v156, v[124:127]
	ds_write_b128 v156, v[120:123] offset:64
	ds_read_b128 v[120:123], v157
	ds_read_b128 v[124:127], v157 offset:16
	ds_write_b128 v156, v[116:119]
	ds_write_b128 v156, v[112:115] offset:64
	ds_read_b128 v[112:115], v157
	ds_read_b128 v[116:119], v157 offset:16
	s_waitcnt vmcnt(15) lgkmcnt(4)
	v_lshlrev_b32_e32 v236, 16, v160
	v_and_b32_e32 v237, 0xffff0000, v160
	v_lshlrev_b32_e32 v238, 16, v161
	v_and_b32_e32 v239, 0xffff0000, v161
	v_lshlrev_b32_e32 v240, 16, v162
	v_and_b32_e32 v241, 0xffff0000, v162
	v_lshlrev_b32_e32 v242, 16, v163
	v_and_b32_e32 v243, 0xffff0000, v163
	v_pk_add_f32 v[120:121], v[120:121], v[236:237]
	v_pk_add_f32 v[122:123], v[122:123], v[238:239]
	v_pk_add_f32 v[124:125], v[124:125], v[240:241]
	v_pk_add_f32 v[126:127], v[126:127], v[242:243]
	v_mul_f32_e32 v236, v121, v121
	v_mul_f32_e32 v237, v123, v123
	v_mul_f32_e32 v238, v125, v125
	v_mul_f32_e32 v239, v127, v127
	v_fmac_f32_e32 v236, v120, v120
	v_fmac_f32_e32 v237, v122, v122
	v_fmac_f32_e32 v238, v124, v124
	v_fmac_f32_e32 v239, v126, v126
	v_cvt_pk_bf16_f32 v120, v120, v121
	v_cvt_pk_bf16_f32 v121, v122, v123
	v_cvt_pk_bf16_f32 v122, v124, v125
	v_cvt_pk_bf16_f32 v123, v126, v127
	v_add_f32_e32 v236, v236, v237
	v_add_f32_e32 v237, v238, v239
	v_add_f32_e32 v124, v236, v237
	global_store_dwordx4 v159, v[120:123], s[28:29]
	ds_write_b128 v156, v[108:111]
	ds_write_b128 v156, v[104:107] offset:64
	ds_read_b128 v[104:107], v157
	ds_read_b128 v[108:111], v157 offset:16
	s_waitcnt vmcnt(15) lgkmcnt(4)
	v_lshlrev_b32_e32 v236, 16, v164
	v_and_b32_e32 v237, 0xffff0000, v164
	v_lshlrev_b32_e32 v238, 16, v165
	v_and_b32_e32 v239, 0xffff0000, v165
	v_lshlrev_b32_e32 v240, 16, v166
	v_and_b32_e32 v241, 0xffff0000, v166
	v_lshlrev_b32_e32 v242, 16, v167
	v_and_b32_e32 v243, 0xffff0000, v167
	v_pk_add_f32 v[112:113], v[112:113], v[236:237]
	v_pk_add_f32 v[114:115], v[114:115], v[238:239]
	v_pk_add_f32 v[116:117], v[116:117], v[240:241]
	v_pk_add_f32 v[118:119], v[118:119], v[242:243]
	v_mul_f32_e32 v236, v113, v113
	v_mul_f32_e32 v237, v115, v115
	v_mul_f32_e32 v238, v117, v117
	v_mul_f32_e32 v239, v119, v119
	v_fmac_f32_e32 v236, v112, v112
	v_fmac_f32_e32 v237, v114, v114
	v_fmac_f32_e32 v238, v116, v116
	v_fmac_f32_e32 v239, v118, v118
	v_cvt_pk_bf16_f32 v112, v112, v113
	v_cvt_pk_bf16_f32 v113, v114, v115
	v_cvt_pk_bf16_f32 v114, v116, v117
	v_cvt_pk_bf16_f32 v115, v118, v119
	v_add_f32_e32 v236, v236, v237
	v_add_f32_e32 v237, v238, v239
	v_add_f32_e32 v116, v236, v237
	global_store_dwordx4 v159, v[112:115], s[28:29] offset:64
	v_add_f32_e32 v117, v124, v116
	s_nop 1
	v_add_f32_dpp v118, v117, v117 quad_perm:[1,0,3,2] row_mask:0xf bank_mask:0xf
	s_nop 1
	v_add_f32_dpp v119, v118, v118 quad_perm:[2,3,0,1] row_mask:0xf bank_mask:0xf
	v_mul_f32_e32 v126, 0x49800000, v119
	v_trunc_f32_e32 v126, v126
	v_mul_f32_e32 v127, 0x2f800000, v126
	v_floor_f32_e32 v127, v127
	v_fmac_f32_e32 v126, 0xcf800000, v127
	v_cvt_u32_f32_e32 v126, v126
	v_cvt_u32_f32_e32 v127, v127
	ds_write_b128 v156, v[100:103]
	ds_write_b128 v156, v[96:99] offset:64
	ds_read_b128 v[96:99], v157
	ds_read_b128 v[100:103], v157 offset:16
	s_waitcnt vmcnt(15) lgkmcnt(4)
	v_lshlrev_b32_e32 v236, 16, v168
	v_and_b32_e32 v237, 0xffff0000, v168
	v_lshlrev_b32_e32 v238, 16, v169
	v_and_b32_e32 v239, 0xffff0000, v169
	v_lshlrev_b32_e32 v240, 16, v170
	v_and_b32_e32 v241, 0xffff0000, v170
	v_lshlrev_b32_e32 v242, 16, v171
	v_and_b32_e32 v243, 0xffff0000, v171
	v_pk_add_f32 v[104:105], v[104:105], v[236:237]
	v_pk_add_f32 v[106:107], v[106:107], v[238:239]
	v_pk_add_f32 v[108:109], v[108:109], v[240:241]
	v_pk_add_f32 v[110:111], v[110:111], v[242:243]
	v_mul_f32_e32 v236, v105, v105
	v_mul_f32_e32 v237, v107, v107
	v_mul_f32_e32 v238, v109, v109
	v_mul_f32_e32 v239, v111, v111
	v_fmac_f32_e32 v236, v104, v104
	v_fmac_f32_e32 v237, v106, v106
	v_fmac_f32_e32 v238, v108, v108
	v_fmac_f32_e32 v239, v110, v110
	v_cvt_pk_bf16_f32 v104, v104, v105
	v_cvt_pk_bf16_f32 v105, v106, v107
	v_cvt_pk_bf16_f32 v106, v108, v109
	v_cvt_pk_bf16_f32 v107, v110, v111
	v_add_f32_e32 v236, v236, v237
	v_add_f32_e32 v237, v238, v239
	v_add_f32_e32 v108, v236, v237
	v_add_u32_e32 v147, 0x10000, v159
	global_store_dwordx4 v147, v[104:107], s[28:29]
	ds_write_b128 v156, v[92:95]
	ds_write_b128 v156, v[88:91] offset:64
	ds_read_b128 v[88:91], v157
	ds_read_b128 v[92:95], v157 offset:16
	s_waitcnt vmcnt(15) lgkmcnt(4)
	v_lshlrev_b32_e32 v236, 16, v172
	v_and_b32_e32 v237, 0xffff0000, v172
	v_lshlrev_b32_e32 v238, 16, v173
	v_and_b32_e32 v239, 0xffff0000, v173
	v_lshlrev_b32_e32 v240, 16, v174
	v_and_b32_e32 v241, 0xffff0000, v174
	v_lshlrev_b32_e32 v242, 16, v175
	v_and_b32_e32 v243, 0xffff0000, v175
	v_pk_add_f32 v[96:97], v[96:97], v[236:237]
	v_pk_add_f32 v[98:99], v[98:99], v[238:239]
	v_pk_add_f32 v[100:101], v[100:101], v[240:241]
	v_pk_add_f32 v[102:103], v[102:103], v[242:243]
	v_mul_f32_e32 v236, v97, v97
	v_mul_f32_e32 v237, v99, v99
	v_mul_f32_e32 v238, v101, v101
	v_mul_f32_e32 v239, v103, v103
	v_fmac_f32_e32 v236, v96, v96
	v_fmac_f32_e32 v237, v98, v98
	v_fmac_f32_e32 v238, v100, v100
	v_fmac_f32_e32 v239, v102, v102
	v_cvt_pk_bf16_f32 v96, v96, v97
	v_cvt_pk_bf16_f32 v97, v98, v99
	v_cvt_pk_bf16_f32 v98, v100, v101
	v_cvt_pk_bf16_f32 v99, v102, v103
	v_add_f32_e32 v236, v236, v237
	v_add_f32_e32 v237, v238, v239
	v_add_f32_e32 v100, v236, v237
	global_store_dwordx4 v147, v[96:99], s[28:29] offset:64
	v_add_f32_e32 v101, v108, v100
	s_nop 1
	v_add_f32_dpp v102, v101, v101 quad_perm:[1,0,3,2] row_mask:0xf bank_mask:0xf
	s_nop 1
	v_add_f32_dpp v103, v102, v102 quad_perm:[2,3,0,1] row_mask:0xf bank_mask:0xf
	v_mul_f32_e32 v110, 0x49800000, v103
	v_trunc_f32_e32 v110, v110
	v_mul_f32_e32 v111, 0x2f800000, v110
	v_floor_f32_e32 v111, v111
	v_fmac_f32_e32 v110, 0xcf800000, v111
	v_cvt_u32_f32_e32 v110, v110
	v_cvt_u32_f32_e32 v111, v111
	ds_write_b128 v156, v[84:87]
	ds_write_b128 v156, v[80:83] offset:64
	ds_read_b128 v[80:83], v157
	ds_read_b128 v[84:87], v157 offset:16
	s_waitcnt vmcnt(15) lgkmcnt(4)
; #define PG8_LAS __attribute__((address_space(3)))
; __device__ __forceinline__ unsigned cvt_pk_bf16(float lo, float hi) { unsigned r; asm volatile("v_cvt_pk_bf16_f32 %0, %1, %2" : "=v"(r) : "v"(lo), "v"(hi)); return r; }
;     __device__ __forceinline__ void operator()(const f32x4 (&acc)[2][2][4][2], const Unit& u, int wr, int wc, int fr, int fq) const {
;     ...
;                 for (int bj = 0; bj < 2; ++bj) {
;                     const size_t off = (size_t)row * 2048 + u.pn * BM + wc * 64 + bj * 32 + 8 * p;
;                     f32x4 b0, b1;
;                     if (BASE_F32) { b0 = *(const f32x4*)((const float*)base + off); b1 = *(const f32x4*)((const float*)base + off + 4); }
;                     else { const u32x4 bb = *(const u32x4*)((const bf16_t*)base + off);
;                         b0 = (f32x4){__uint_as_float(bb.x << 16), __uint_as_float(bb.x & 0xffff0000u), __uint_as_float(bb.y << 16), __uint_as_float(bb.y & 0xffff0000u)};
;                         b1 = (f32x4){__uint_as_float(bb.z << 16), __uint_as_float(bb.z & 0xffff0000u), __uint_as_float(bb.w << 16), __uint_as_float(bb.w & 0xffff0000u)}; }
; #pragma unroll
;                     for (int n = 0; n < 2; ++n) *(PG8_LAS f32x4*)(stg + fr * STG_ROW + n * 64 + fq * 16) = acc[ai][bj][m][n];
;                     const f32x4 v0 = *(const PG8_LAS f32x4*)(stg + r * STG_ROW + p * 32) + b0, v1 = *(const PG8_LAS f32x4*)(stg + r * STG_ROW + p * 32 + 16) + b1;
;                     q += ((v0[0] * v0[0] + v0[1] * v0[1]) + (v0[2] * v0[2] + v0[3] * v0[3])) + ((v1[0] * v1[0] + v1[1] * v1[1]) + (v1[2] * v1[2] + v1[3] * v1[3]));
;                     u32x4 w; w.x = cvt_pk_bf16(v0[0], v0[1]); w.y = cvt_pk_bf16(v0[2], v0[3]); w.z = cvt_pk_bf16(v1[0], v1[1]); w.w = cvt_pk_bf16(v1[2], v1[3]);
;                     *(u32x4*)(out + off) = w;
;                 }
;                 q += __shfl_xor(q, 1); q += __shfl_xor(q, 2);
;                 if (p == 0) atomicAdd(ssn + row, (u64)(q * SS_SCALE));
	v_lshlrev_b32_e32 v236, 16, v176
	v_and_b32_e32 v237, 0xffff0000, v176
	v_lshlrev_b32_e32 v238, 16, v177
	v_and_b32_e32 v239, 0xffff0000, v177
	v_lshlrev_b32_e32 v240, 16, v178
	v_and_b32_e32 v241, 0xffff0000, v178
	v_lshlrev_b32_e32 v242, 16, v179
	v_and_b32_e32 v243, 0xffff0000, v179
	v_pk_add_f32 v[88:89], v[88:89], v[236:237]
	v_pk_add_f32 v[90:91], v[90:91], v[238:239]
	v_pk_add_f32 v[92:93], v[92:93], v[240:241]
	v_pk_add_f32 v[94:95], v[94:95], v[242:243]
	v_mul_f32_e32 v236, v89, v89
	v_mul_f32_e32 v237, v91, v91
	v_mul_f32_e32 v238, v93, v93
	v_mul_f32_e32 v239, v95, v95
	v_fmac_f32_e32 v236, v88, v88
	v_fmac_f32_e32 v237, v90, v90
	v_fmac_f32_e32 v238, v92, v92
	v_fmac_f32_e32 v239, v94, v94
	v_cvt_pk_bf16_f32 v88, v88, v89
	v_cvt_pk_bf16_f32 v89, v90, v91
	v_cvt_pk_bf16_f32 v90, v92, v93
	v_cvt_pk_bf16_f32 v91, v94, v95
	v_add_f32_e32 v236, v236, v237
	v_add_f32_e32 v237, v238, v239
	v_add_f32_e32 v92, v236, v237
	v_add_u32_e32 v146, 0x20000, v159
	global_store_dwordx4 v146, v[88:91], s[28:29]
	ds_write_b128 v156, v[76:79]
	ds_write_b128 v156, v[72:75] offset:64
	ds_read_b128 v[72:75], v157
	ds_read_b128 v[76:79], v157 offset:16
	s_waitcnt vmcnt(15) lgkmcnt(4)
	v_lshlrev_b32_e32 v236, 16, v180
	v_and_b32_e32 v237, 0xffff0000, v180
	v_lshlrev_b32_e32 v238, 16, v181
	v_and_b32_e32 v239, 0xffff0000, v181
	v_lshlrev_b32_e32 v240, 16, v182
	v_and_b32_e32 v241, 0xffff0000, v182
	v_lshlrev_b32_e32 v242, 16, v183
	v_and_b32_e32 v243, 0xffff0000, v183
	v_pk_add_f32 v[80:81], v[80:81], v[236:237]
	v_pk_add_f32 v[82:83], v[82:83], v[238:239]
	v_pk_add_f32 v[84:85], v[84:85], v[240:241]
	v_pk_add_f32 v[86:87], v[86:87], v[242:243]
	v_mul_f32_e32 v236, v81, v81
	v_mul_f32_e32 v237, v83, v83
	v_mul_f32_e32 v238, v85, v85
	v_mul_f32_e32 v239, v87, v87
	v_fmac_f32_e32 v236, v80, v80
	v_fmac_f32_e32 v237, v82, v82
	v_fmac_f32_e32 v238, v84, v84
	v_fmac_f32_e32 v239, v86, v86
	v_cvt_pk_bf16_f32 v80, v80, v81
	v_cvt_pk_bf16_f32 v81, v82, v83
	v_cvt_pk_bf16_f32 v82, v84, v85
	v_cvt_pk_bf16_f32 v83, v86, v87
	v_add_f32_e32 v236, v236, v237
	v_add_f32_e32 v237, v238, v239
	v_add_f32_e32 v84, v236, v237
	global_store_dwordx4 v146, v[80:83], s[28:29] offset:64
	v_add_f32_e32 v85, v92, v84
	s_nop 1
	v_add_f32_dpp v86, v85, v85 quad_perm:[1,0,3,2] row_mask:0xf bank_mask:0xf
	s_nop 1
	v_add_f32_dpp v87, v86, v86 quad_perm:[2,3,0,1] row_mask:0xf bank_mask:0xf
	v_mul_f32_e32 v94, 0x49800000, v87
	v_trunc_f32_e32 v94, v94
	v_mul_f32_e32 v95, 0x2f800000, v94
	v_floor_f32_e32 v95, v95
	v_fmac_f32_e32 v94, 0xcf800000, v95
	v_cvt_u32_f32_e32 v94, v94
	v_cvt_u32_f32_e32 v95, v95
	ds_write_b128 v156, v[68:71]
	ds_write_b128 v156, v[64:67] offset:64
	ds_read_b128 v[64:67], v157
	ds_read_b128 v[68:71], v157 offset:16
	s_waitcnt vmcnt(15) lgkmcnt(4)
	v_lshlrev_b32_e32 v236, 16, v184
	v_and_b32_e32 v237, 0xffff0000, v184
	v_lshlrev_b32_e32 v238, 16, v185
	v_and_b32_e32 v239, 0xffff0000, v185
	v_lshlrev_b32_e32 v240, 16, v186
	v_and_b32_e32 v241, 0xffff0000, v186
	v_lshlrev_b32_e32 v242, 16, v187
	v_and_b32_e32 v243, 0xffff0000, v187
	v_pk_add_f32 v[72:73], v[72:73], v[236:237]
	v_pk_add_f32 v[74:75], v[74:75], v[238:239]
	v_pk_add_f32 v[76:77], v[76:77], v[240:241]
	v_pk_add_f32 v[78:79], v[78:79], v[242:243]
	v_mul_f32_e32 v236, v73, v73
	v_mul_f32_e32 v237, v75, v75
	v_mul_f32_e32 v238, v77, v77
	v_mul_f32_e32 v239, v79, v79
	v_fmac_f32_e32 v236, v72, v72
	v_fmac_f32_e32 v237, v74, v74
	v_fmac_f32_e32 v238, v76, v76
	v_fmac_f32_e32 v239, v78, v78
	v_cvt_pk_bf16_f32 v72, v72, v73
	v_cvt_pk_bf16_f32 v73, v74, v75
	v_cvt_pk_bf16_f32 v74, v76, v77
	v_cvt_pk_bf16_f32 v75, v78, v79
	v_add_f32_e32 v236, v236, v237
	v_add_f32_e32 v237, v238, v239
	v_add_f32_e32 v76, v236, v237
	v_add_u32_e32 v147, 0x30000, v159
	global_store_dwordx4 v147, v[72:75], s[28:29]
	ds_write_b128 v156, v[60:63]
	ds_write_b128 v156, v[56:59] offset:64
	ds_read_b128 v[56:59], v157
	ds_read_b128 v[60:63], v157 offset:16
	s_waitcnt vmcnt(15) lgkmcnt(4)
	v_lshlrev_b32_e32 v236, 16, v188
	v_and_b32_e32 v237, 0xffff0000, v188
	v_lshlrev_b32_e32 v238, 16, v189
	v_and_b32_e32 v239, 0xffff0000, v189
	v_lshlrev_b32_e32 v240, 16, v190
	v_and_b32_e32 v241, 0xffff0000, v190
	v_lshlrev_b32_e32 v242, 16, v191
	v_and_b32_e32 v243, 0xffff0000, v191
	v_pk_add_f32 v[64:65], v[64:65], v[236:237]
	v_pk_add_f32 v[66:67], v[66:67], v[238:239]
	v_pk_add_f32 v[68:69], v[68:69], v[240:241]
	v_pk_add_f32 v[70:71], v[70:71], v[242:243]
	v_mul_f32_e32 v236, v65, v65
	v_mul_f32_e32 v237, v67, v67
	v_mul_f32_e32 v238, v69, v69
	v_mul_f32_e32 v239, v71, v71
	v_fmac_f32_e32 v236, v64, v64
	v_fmac_f32_e32 v237, v66, v66
	v_fmac_f32_e32 v238, v68, v68
	v_fmac_f32_e32 v239, v70, v70
	v_cvt_pk_bf16_f32 v64, v64, v65
	v_cvt_pk_bf16_f32 v65, v66, v67
	v_cvt_pk_bf16_f32 v66, v68, v69
	v_cvt_pk_bf16_f32 v67, v70, v71
	v_add_f32_e32 v236, v236, v237
	v_add_f32_e32 v237, v238, v239
	v_add_f32_e32 v68, v236, v237
	global_store_dwordx4 v147, v[64:67], s[28:29] offset:64
	v_add_f32_e32 v69, v76, v68
	s_nop 1
	v_add_f32_dpp v70, v69, v69 quad_perm:[1,0,3,2] row_mask:0xf bank_mask:0xf
	s_nop 1
	v_add_f32_dpp v71, v70, v70 quad_perm:[2,3,0,1] row_mask:0xf bank_mask:0xf
	v_mul_f32_e32 v78, 0x49800000, v71
	v_trunc_f32_e32 v78, v78
	v_mul_f32_e32 v79, 0x2f800000, v78
	v_floor_f32_e32 v79, v79
	v_fmac_f32_e32 v78, 0xcf800000, v79
	v_cvt_u32_f32_e32 v78, v78
	v_cvt_u32_f32_e32 v79, v79
	ds_write_b128 v156, v[52:55]
	ds_write_b128 v156, v[48:51] offset:64
	ds_read_b128 v[48:51], v157
	ds_read_b128 v[52:55], v157 offset:16
	s_waitcnt vmcnt(15) lgkmcnt(4)
; #define PG8_LAS __attribute__((address_space(3)))
; __device__ __forceinline__ unsigned cvt_pk_bf16(float lo, float hi) { unsigned r; asm volatile("v_cvt_pk_bf16_f32 %0, %1, %2" : "=v"(r) : "v"(lo), "v"(hi)); return r; }
;     __device__ __forceinline__ void operator()(const f32x4 (&acc)[2][2][4][2], const Unit& u, int wr, int wc, int fr, int fq) const {
;     ...
;                 for (int bj = 0; bj < 2; ++bj) {
;                     const size_t off = (size_t)row * 2048 + u.pn * BM + wc * 64 + bj * 32 + 8 * p;
;                     f32x4 b0, b1;
;                     if (BASE_F32) { b0 = *(const f32x4*)((const float*)base + off); b1 = *(const f32x4*)((const float*)base + off + 4); }
;                     else { const u32x4 bb = *(const u32x4*)((const bf16_t*)base + off);
;                         b0 = (f32x4){__uint_as_float(bb.x << 16), __uint_as_float(bb.x & 0xffff0000u), __uint_as_float(bb.y << 16), __uint_as_float(bb.y & 0xffff0000u)};
;                         b1 = (f32x4){__uint_as_float(bb.z << 16), __uint_as_float(bb.z & 0xffff0000u), __uint_as_float(bb.w << 16), __uint_as_float(bb.w & 0xffff0000u)}; }
; #pragma unroll
;                     for (int n = 0; n < 2; ++n) *(PG8_LAS f32x4*)(stg + fr * STG_ROW + n * 64 + fq * 16) = acc[ai][bj][m][n];
;                     const f32x4 v0 = *(const PG8_LAS f32x4*)(stg + r * STG_ROW + p * 32) + b0, v1 = *(const PG8_LAS f32x4*)(stg + r * STG_ROW + p * 32 + 16) + b1;
;                     q += ((v0[0] * v0[0] + v0[1] * v0[1]) + (v0[2] * v0[2] + v0[3] * v0[3])) + ((v1[0] * v1[0] + v1[1] * v1[1]) + (v1[2] * v1[2] + v1[3] * v1[3]));
;                     u32x4 w; w.x = cvt_pk_bf16(v0[0], v0[1]); w.y = cvt_pk_bf16(v0[2], v0[3]); w.z = cvt_pk_bf16(v1[0], v1[1]); w.w = cvt_pk_bf16(v1[2], v1[3]);
;                     *(u32x4*)(out + off) = w;
;                 }
;                 q += __shfl_xor(q, 1); q += __shfl_xor(q, 2);
;                 if (p == 0) atomicAdd(ssn + row, (u64)(q * SS_SCALE));
	v_lshlrev_b32_e32 v236, 16, v192
	v_and_b32_e32 v237, 0xffff0000, v192
	v_lshlrev_b32_e32 v238, 16, v193
	v_and_b32_e32 v239, 0xffff0000, v193
	v_lshlrev_b32_e32 v240, 16, v194
	v_and_b32_e32 v241, 0xffff0000, v194
	v_lshlrev_b32_e32 v242, 16, v195
	v_and_b32_e32 v243, 0xffff0000, v195
	v_pk_add_f32 v[56:57], v[56:57], v[236:237]
	v_pk_add_f32 v[58:59], v[58:59], v[238:239]
	v_pk_add_f32 v[60:61], v[60:61], v[240:241]
	v_pk_add_f32 v[62:63], v[62:63], v[242:243]
	v_mul_f32_e32 v236, v57, v57
	v_mul_f32_e32 v237, v59, v59
	v_mul_f32_e32 v238, v61, v61
	v_mul_f32_e32 v239, v63, v63
	v_fmac_f32_e32 v236, v56, v56
	v_fmac_f32_e32 v237, v58, v58
	v_fmac_f32_e32 v238, v60, v60
	v_fmac_f32_e32 v239, v62, v62
	v_cvt_pk_bf16_f32 v56, v56, v57
	v_cvt_pk_bf16_f32 v57, v58, v59
	v_cvt_pk_bf16_f32 v58, v60, v61
	v_cvt_pk_bf16_f32 v59, v62, v63
	v_add_f32_e32 v236, v236, v237
	v_add_f32_e32 v237, v238, v239
	v_add_f32_e32 v60, v236, v237
	v_add_u32_e32 v146, 0x80000, v159
	global_store_dwordx4 v146, v[56:59], s[28:29]
	ds_write_b128 v156, v[44:47]
	ds_write_b128 v156, v[40:43] offset:64
	ds_read_b128 v[40:43], v157
	ds_read_b128 v[44:47], v157 offset:16
	s_waitcnt vmcnt(15) lgkmcnt(4)
	v_lshlrev_b32_e32 v236, 16, v196
	v_and_b32_e32 v237, 0xffff0000, v196
	v_lshlrev_b32_e32 v238, 16, v197
	v_and_b32_e32 v239, 0xffff0000, v197
	v_lshlrev_b32_e32 v240, 16, v198
	v_and_b32_e32 v241, 0xffff0000, v198
	v_lshlrev_b32_e32 v242, 16, v199
	v_and_b32_e32 v243, 0xffff0000, v199
	v_pk_add_f32 v[48:49], v[48:49], v[236:237]
	v_pk_add_f32 v[50:51], v[50:51], v[238:239]
	v_pk_add_f32 v[52:53], v[52:53], v[240:241]
	v_pk_add_f32 v[54:55], v[54:55], v[242:243]
	v_mul_f32_e32 v236, v49, v49
	v_mul_f32_e32 v237, v51, v51
	v_mul_f32_e32 v238, v53, v53
	v_mul_f32_e32 v239, v55, v55
	v_fmac_f32_e32 v236, v48, v48
	v_fmac_f32_e32 v237, v50, v50
	v_fmac_f32_e32 v238, v52, v52
	v_fmac_f32_e32 v239, v54, v54
	v_cvt_pk_bf16_f32 v48, v48, v49
	v_cvt_pk_bf16_f32 v49, v50, v51
	v_cvt_pk_bf16_f32 v50, v52, v53
	v_cvt_pk_bf16_f32 v51, v54, v55
	v_add_f32_e32 v236, v236, v237
	v_add_f32_e32 v237, v238, v239
	v_add_f32_e32 v52, v236, v237
	global_store_dwordx4 v146, v[48:51], s[28:29] offset:64
	v_add_f32_e32 v53, v60, v52
	s_nop 1
	v_add_f32_dpp v54, v53, v53 quad_perm:[1,0,3,2] row_mask:0xf bank_mask:0xf
	s_nop 1
	v_add_f32_dpp v55, v54, v54 quad_perm:[2,3,0,1] row_mask:0xf bank_mask:0xf
	v_mul_f32_e32 v62, 0x49800000, v55
	v_trunc_f32_e32 v62, v62
	v_mul_f32_e32 v63, 0x2f800000, v62
	v_floor_f32_e32 v63, v63
	v_fmac_f32_e32 v62, 0xcf800000, v63
	v_cvt_u32_f32_e32 v62, v62
	v_cvt_u32_f32_e32 v63, v63
	ds_write_b128 v156, v[36:39]
	ds_write_b128 v156, v[32:35] offset:64
	ds_read_b128 v[32:35], v157
	ds_read_b128 v[36:39], v157 offset:16
	s_waitcnt vmcnt(15) lgkmcnt(4)
	v_lshlrev_b32_e32 v236, 16, v200
	v_and_b32_e32 v237, 0xffff0000, v200
	v_lshlrev_b32_e32 v238, 16, v201
	v_and_b32_e32 v239, 0xffff0000, v201
	v_lshlrev_b32_e32 v240, 16, v202
	v_and_b32_e32 v241, 0xffff0000, v202
	v_lshlrev_b32_e32 v242, 16, v203
	v_and_b32_e32 v243, 0xffff0000, v203
	v_pk_add_f32 v[40:41], v[40:41], v[236:237]
	v_pk_add_f32 v[42:43], v[42:43], v[238:239]
	v_pk_add_f32 v[44:45], v[44:45], v[240:241]
	v_pk_add_f32 v[46:47], v[46:47], v[242:243]
	v_mul_f32_e32 v236, v41, v41
	v_mul_f32_e32 v237, v43, v43
	v_mul_f32_e32 v238, v45, v45
	v_mul_f32_e32 v239, v47, v47
	v_fmac_f32_e32 v236, v40, v40
	v_fmac_f32_e32 v237, v42, v42
	v_fmac_f32_e32 v238, v44, v44
	v_fmac_f32_e32 v239, v46, v46
	v_cvt_pk_bf16_f32 v40, v40, v41
	v_cvt_pk_bf16_f32 v41, v42, v43
	v_cvt_pk_bf16_f32 v42, v44, v45
	v_cvt_pk_bf16_f32 v43, v46, v47
	v_add_f32_e32 v236, v236, v237
	v_add_f32_e32 v237, v238, v239
	v_add_f32_e32 v44, v236, v237
	v_add_u32_e32 v147, 0x90000, v159
	global_store_dwordx4 v147, v[40:43], s[28:29]
	ds_write_b128 v156, v[28:31]
	ds_write_b128 v156, v[24:27] offset:64
	ds_read_b128 v[24:27], v157
	ds_read_b128 v[28:31], v157 offset:16
	s_waitcnt vmcnt(15) lgkmcnt(4)
	v_lshlrev_b32_e32 v236, 16, v204
	v_and_b32_e32 v237, 0xffff0000, v204
	v_lshlrev_b32_e32 v238, 16, v205
	v_and_b32_e32 v239, 0xffff0000, v205
	v_lshlrev_b32_e32 v240, 16, v206
	v_and_b32_e32 v241, 0xffff0000, v206
	v_lshlrev_b32_e32 v242, 16, v207
	v_and_b32_e32 v243, 0xffff0000, v207
	v_pk_add_f32 v[32:33], v[32:33], v[236:237]
	v_pk_add_f32 v[34:35], v[34:35], v[238:239]
	v_pk_add_f32 v[36:37], v[36:37], v[240:241]
	v_pk_add_f32 v[38:39], v[38:39], v[242:243]
	v_mul_f32_e32 v236, v33, v33
	v_mul_f32_e32 v237, v35, v35
	v_mul_f32_e32 v238, v37, v37
	v_mul_f32_e32 v239, v39, v39
	v_fmac_f32_e32 v236, v32, v32
	v_fmac_f32_e32 v237, v34, v34
	v_fmac_f32_e32 v238, v36, v36
	v_fmac_f32_e32 v239, v38, v38
	v_cvt_pk_bf16_f32 v32, v32, v33
	v_cvt_pk_bf16_f32 v33, v34, v35
	v_cvt_pk_bf16_f32 v34, v36, v37
	v_cvt_pk_bf16_f32 v35, v38, v39
	v_add_f32_e32 v236, v236, v237
	v_add_f32_e32 v237, v238, v239
	v_add_f32_e32 v36, v236, v237
	global_store_dwordx4 v147, v[32:35], s[28:29] offset:64
	v_add_f32_e32 v37, v44, v36
	s_nop 1
	v_add_f32_dpp v38, v37, v37 quad_perm:[1,0,3,2] row_mask:0xf bank_mask:0xf
	s_nop 1
	v_add_f32_dpp v39, v38, v38 quad_perm:[2,3,0,1] row_mask:0xf bank_mask:0xf
	v_mul_f32_e32 v46, 0x49800000, v39
	v_trunc_f32_e32 v46, v46
	v_mul_f32_e32 v47, 0x2f800000, v46
	v_floor_f32_e32 v47, v47
	v_fmac_f32_e32 v46, 0xcf800000, v47
	v_cvt_u32_f32_e32 v46, v46
	v_cvt_u32_f32_e32 v47, v47
	ds_write_b128 v156, v[20:23]
	ds_write_b128 v156, v[16:19] offset:64
	ds_read_b128 v[16:19], v157
	ds_read_b128 v[20:23], v157 offset:16
	s_waitcnt vmcnt(15) lgkmcnt(4)
; #define PG8_LAS __attribute__((address_space(3)))
; __device__ __forceinline__ unsigned cvt_pk_bf16(float lo, float hi) { unsigned r; asm volatile("v_cvt_pk_bf16_f32 %0, %1, %2" : "=v"(r) : "v"(lo), "v"(hi)); return r; }
;     __device__ __forceinline__ void operator()(const f32x4 (&acc)[2][2][4][2], const Unit& u, int wr, int wc, int fr, int fq) const {
;     ...
;                 for (int bj = 0; bj < 2; ++bj) {
;                     const size_t off = (size_t)row * 2048 + u.pn * BM + wc * 64 + bj * 32 + 8 * p;
;                     f32x4 b0, b1;
;                     if (BASE_F32) { b0 = *(const f32x4*)((const float*)base + off); b1 = *(const f32x4*)((const float*)base + off + 4); }
;                     else { const u32x4 bb = *(const u32x4*)((const bf16_t*)base + off);
;                         b0 = (f32x4){__uint_as_float(bb.x << 16), __uint_as_float(bb.x & 0xffff0000u), __uint_as_float(bb.y << 16), __uint_as_float(bb.y & 0xffff0000u)};
;                         b1 = (f32x4){__uint_as_float(bb.z << 16), __uint_as_float(bb.z & 0xffff0000u), __uint_as_float(bb.w << 16), __uint_as_float(bb.w & 0xffff0000u)}; }
; #pragma unroll
;                     for (int n = 0; n < 2; ++n) *(PG8_LAS f32x4*)(stg + fr * STG_ROW + n * 64 + fq * 16) = acc[ai][bj][m][n];
;                     const f32x4 v0 = *(const PG8_LAS f32x4*)(stg + r * STG_ROW + p * 32) + b0, v1 = *(const PG8_LAS f32x4*)(stg + r * STG_ROW + p * 32 + 16) + b1;
;                     q += ((v0[0] * v0[0] + v0[1] * v0[1]) + (v0[2] * v0[2] + v0[3] * v0[3])) + ((v1[0] * v1[0] + v1[1] * v1[1]) + (v1[2] * v1[2] + v1[3] * v1[3]));
;                     u32x4 w; w.x = cvt_pk_bf16(v0[0], v0[1]); w.y = cvt_pk_bf16(v0[2], v0[3]); w.z = cvt_pk_bf16(v1[0], v1[1]); w.w = cvt_pk_bf16(v1[2], v1[3]);
;                     *(u32x4*)(out + off) = w;
;                 }
;                 q += __shfl_xor(q, 1); q += __shfl_xor(q, 2);
;                 if (p == 0) atomicAdd(ssn + row, (u64)(q * SS_SCALE));
	v_lshlrev_b32_e32 v236, 16, v212
	v_and_b32_e32 v237, 0xffff0000, v212
	v_lshlrev_b32_e32 v238, 16, v213
	v_and_b32_e32 v239, 0xffff0000, v213
	v_lshlrev_b32_e32 v240, 16, v214
	v_and_b32_e32 v241, 0xffff0000, v214
	v_lshlrev_b32_e32 v242, 16, v215
	v_and_b32_e32 v243, 0xffff0000, v215
	v_pk_add_f32 v[24:25], v[24:25], v[236:237]
	v_pk_add_f32 v[26:27], v[26:27], v[238:239]
	v_pk_add_f32 v[28:29], v[28:29], v[240:241]
	v_pk_add_f32 v[30:31], v[30:31], v[242:243]
	v_mul_f32_e32 v236, v25, v25
	v_mul_f32_e32 v237, v27, v27
	v_mul_f32_e32 v238, v29, v29
	v_mul_f32_e32 v239, v31, v31
	v_fmac_f32_e32 v236, v24, v24
	v_fmac_f32_e32 v237, v26, v26
	v_fmac_f32_e32 v238, v28, v28
	v_fmac_f32_e32 v239, v30, v30
	v_cvt_pk_bf16_f32 v24, v24, v25
	v_cvt_pk_bf16_f32 v25, v26, v27
	v_cvt_pk_bf16_f32 v26, v28, v29
	v_cvt_pk_bf16_f32 v27, v30, v31
	v_add_f32_e32 v236, v236, v237
	v_add_f32_e32 v237, v238, v239
	v_add_f32_e32 v28, v236, v237
	v_add_u32_e32 v146, 0xa0000, v159
	global_store_dwordx4 v146, v[24:27], s[28:29]
	ds_write_b128 v156, v[12:15]
	ds_write_b128 v156, v[8:11] offset:64
	ds_read_b128 v[8:11], v157
	ds_read_b128 v[12:15], v157 offset:16
	s_waitcnt vmcnt(15) lgkmcnt(4)
	v_lshlrev_b32_e32 v236, 16, v216
	v_and_b32_e32 v237, 0xffff0000, v216
	v_lshlrev_b32_e32 v238, 16, v217
	v_and_b32_e32 v239, 0xffff0000, v217
	v_lshlrev_b32_e32 v240, 16, v218
	v_and_b32_e32 v241, 0xffff0000, v218
	v_lshlrev_b32_e32 v242, 16, v219
	v_and_b32_e32 v243, 0xffff0000, v219
	v_pk_add_f32 v[16:17], v[16:17], v[236:237]
	v_pk_add_f32 v[18:19], v[18:19], v[238:239]
	v_pk_add_f32 v[20:21], v[20:21], v[240:241]
	v_pk_add_f32 v[22:23], v[22:23], v[242:243]
	v_mul_f32_e32 v236, v17, v17
	v_mul_f32_e32 v237, v19, v19
	v_mul_f32_e32 v238, v21, v21
	v_mul_f32_e32 v239, v23, v23
	v_fmac_f32_e32 v236, v16, v16
	v_fmac_f32_e32 v237, v18, v18
	v_fmac_f32_e32 v238, v20, v20
	v_fmac_f32_e32 v239, v22, v22
	v_cvt_pk_bf16_f32 v16, v16, v17
	v_cvt_pk_bf16_f32 v17, v18, v19
	v_cvt_pk_bf16_f32 v18, v20, v21
	v_cvt_pk_bf16_f32 v19, v22, v23
	v_add_f32_e32 v236, v236, v237
	v_add_f32_e32 v237, v238, v239
	v_add_f32_e32 v20, v236, v237
	global_store_dwordx4 v146, v[16:19], s[28:29] offset:64
	v_add_f32_e32 v21, v28, v20
	s_nop 1
	v_add_f32_dpp v22, v21, v21 quad_perm:[1,0,3,2] row_mask:0xf bank_mask:0xf
	s_nop 1
	v_add_f32_dpp v23, v22, v22 quad_perm:[2,3,0,1] row_mask:0xf bank_mask:0xf
	v_mul_f32_e32 v30, 0x49800000, v23
	v_trunc_f32_e32 v30, v30
	v_mul_f32_e32 v31, 0x2f800000, v30
	v_floor_f32_e32 v31, v31
	v_fmac_f32_e32 v30, 0xcf800000, v31
	v_cvt_u32_f32_e32 v30, v30
	v_cvt_u32_f32_e32 v31, v31
	ds_write_b128 v156, v[4:7]
	ds_write_b128 v156, v[0:3] offset:64
	ds_read_b128 v[0:3], v157
	ds_read_b128 v[4:7], v157 offset:16
	s_waitcnt vmcnt(15) lgkmcnt(4)
	v_lshlrev_b32_e32 v236, 16, v220
	v_and_b32_e32 v237, 0xffff0000, v220
	v_lshlrev_b32_e32 v238, 16, v221
	v_and_b32_e32 v239, 0xffff0000, v221
	v_lshlrev_b32_e32 v240, 16, v222
	v_and_b32_e32 v241, 0xffff0000, v222
	v_lshlrev_b32_e32 v242, 16, v223
	v_and_b32_e32 v243, 0xffff0000, v223
	v_pk_add_f32 v[8:9], v[8:9], v[236:237]
	v_pk_add_f32 v[10:11], v[10:11], v[238:239]
	v_pk_add_f32 v[12:13], v[12:13], v[240:241]
	v_pk_add_f32 v[14:15], v[14:15], v[242:243]
	v_mul_f32_e32 v236, v9, v9
	v_mul_f32_e32 v237, v11, v11
	v_mul_f32_e32 v238, v13, v13
	v_mul_f32_e32 v239, v15, v15
	v_fmac_f32_e32 v236, v8, v8
	v_fmac_f32_e32 v237, v10, v10
	v_fmac_f32_e32 v238, v12, v12
	v_fmac_f32_e32 v239, v14, v14
	v_cvt_pk_bf16_f32 v8, v8, v9
	v_cvt_pk_bf16_f32 v9, v10, v11
	v_cvt_pk_bf16_f32 v10, v12, v13
	v_cvt_pk_bf16_f32 v11, v14, v15
	v_add_f32_e32 v236, v236, v237
	v_add_f32_e32 v237, v238, v239
	v_add_f32_e32 v12, v236, v237
	v_add_u32_e32 v147, 0xb0000, v159
	global_store_dwordx4 v147, v[8:11], s[28:29]
	s_waitcnt vmcnt(15) lgkmcnt(0)
	v_lshlrev_b32_e32 v236, 16, v224
	v_and_b32_e32 v237, 0xffff0000, v224
	v_lshlrev_b32_e32 v238, 16, v225
	v_and_b32_e32 v239, 0xffff0000, v225
	v_lshlrev_b32_e32 v240, 16, v226
	v_and_b32_e32 v241, 0xffff0000, v226
	v_lshlrev_b32_e32 v242, 16, v227
	v_and_b32_e32 v243, 0xffff0000, v227
	v_pk_add_f32 v[0:1], v[0:1], v[236:237]
	v_pk_add_f32 v[2:3], v[2:3], v[238:239]
	v_pk_add_f32 v[4:5], v[4:5], v[240:241]
	v_pk_add_f32 v[6:7], v[6:7], v[242:243]
	v_mul_f32_e32 v236, v1, v1
	v_mul_f32_e32 v237, v3, v3
	v_mul_f32_e32 v238, v5, v5
	v_mul_f32_e32 v239, v7, v7
	v_fmac_f32_e32 v236, v0, v0
	v_fmac_f32_e32 v237, v2, v2
	v_fmac_f32_e32 v238, v4, v4
	v_fmac_f32_e32 v239, v6, v6
	v_cvt_pk_bf16_f32 v0, v0, v1
	v_cvt_pk_bf16_f32 v1, v2, v3
	v_cvt_pk_bf16_f32 v2, v4, v5
	v_cvt_pk_bf16_f32 v3, v6, v7
	v_add_f32_e32 v236, v236, v237
	v_add_f32_e32 v237, v238, v239
	v_add_f32_e32 v4, v236, v237
	global_store_dwordx4 v147, v[0:3], s[28:29] offset:64
	v_add_f32_e32 v5, v12, v4
	s_nop 1
	v_add_f32_dpp v6, v5, v5 quad_perm:[1,0,3,2] row_mask:0xf bank_mask:0xf
	s_nop 1
	v_add_f32_dpp v7, v6, v6 quad_perm:[2,3,0,1] row_mask:0xf bank_mask:0xf
	v_mul_f32_e32 v14, 0x49800000, v7
	v_trunc_f32_e32 v14, v14
	v_mul_f32_e32 v15, 0x2f800000, v14
	v_floor_f32_e32 v15, v15
	v_fmac_f32_e32 v14, 0xcf800000, v15
	v_cvt_u32_f32_e32 v14, v14
	v_cvt_u32_f32_e32 v15, v15
	v_and_b32_e32 v236, 3, v252
	v_lshl_add_u32 v237, v236, 7, v208
	v_cmp_eq_u32_e64 s[100:101], 1, v236
	s_nop 1
	v_cndmask_b32_e64 v126, v126, v110, s[100:101]
	v_cndmask_b32_e64 v127, v127, v111, s[100:101]
	v_cmp_eq_u32_e64 s[100:101], 2, v236
	s_nop 1
	v_cndmask_b32_e64 v126, v126, v94, s[100:101]
	v_cndmask_b32_e64 v127, v127, v95, s[100:101]
	v_cmp_eq_u32_e64 s[100:101], 3, v236
	s_nop 1
	v_cndmask_b32_e64 v126, v126, v78, s[100:101]
	v_cndmask_b32_e64 v127, v127, v79, s[100:101]
	global_atomic_add_x2 v237, v[126:127], s[12:13]
	v_cmp_eq_u32_e64 s[100:101], 1, v236
	s_nop 1
	v_cndmask_b32_e64 v62, v62, v46, s[100:101]
	v_cndmask_b32_e64 v63, v63, v47, s[100:101]
	v_cmp_eq_u32_e64 s[100:101], 2, v236
	s_nop 1
	v_cndmask_b32_e64 v62, v62, v30, s[100:101]
	v_cndmask_b32_e64 v63, v63, v31, s[100:101]
	v_cmp_eq_u32_e64 s[100:101], 3, v236
	s_nop 1
	v_cndmask_b32_e64 v62, v62, v14, s[100:101]
	v_cndmask_b32_e64 v63, v63, v15, s[100:101]
	global_atomic_add_x2 v237, v[62:63], s[12:13] offset:1024
	s_andn2_b64 vcc, exec, s[10:11]
	s_mov_b64 s[10:11], -1
	s_cbranch_vccnz .LBB0_759
	s_andn2_b64 vcc, exec, s[44:45]
	s_cbranch_vccnz .LBB0_758
	s_mov_b32 s98, 1
	s_branch .LBB0_758

; #define PG8_LAS __attribute__((address_space(3)))
; __device__ __forceinline__ unsigned cvt_pk_bf16(float lo, float hi) { unsigned r; asm volatile("v_cvt_pk_bf16_f32 %0, %1, %2" : "=v"(r) : "v"(lo), "v"(hi)); return r; }
;     __device__ __forceinline__ void operator()(const f32x4 (&acc)[2][2][4][2], const Unit& u, int wr, int wc, int fr, int fq) const {
;     ...
;                 for (int bj = 0; bj < 2; ++bj) {
;                     const size_t off = (size_t)row * 2048 + u.pn * BM + wc * 64 + bj * 32 + 8 * p;
;                     f32x4 b0, b1;
;                     if (BASE_F32) { b0 = *(const f32x4*)((const float*)base + off); b1 = *(const f32x4*)((const float*)base + off + 4); }
;                     else { const u32x4 bb = *(const u32x4*)((const bf16_t*)base + off);
;                         b0 = (f32x4){__uint_as_float(bb.x << 16), __uint_as_float(bb.x & 0xffff0000u), __uint_as_float(bb.y << 16), __uint_as_float(bb.y & 0xffff0000u)};
;                         b1 = (f32x4){__uint_as_float(bb.z << 16), __uint_as_float(bb.z & 0xffff0000u), __uint_as_float(bb.w << 16), __uint_as_float(bb.w & 0xffff0000u)}; }
; #pragma unroll
;                     for (int n = 0; n < 2; ++n) *(PG8_LAS f32x4*)(stg + fr * STG_ROW + n * 64 + fq * 16) = acc[ai][bj][m][n];
;                     const f32x4 v0 = *(const PG8_LAS f32x4*)(stg + r * STG_ROW + p * 32) + b0, v1 = *(const PG8_LAS f32x4*)(stg + r * STG_ROW + p * 32 + 16) + b1;
;                     q += ((v0[0] * v0[0] + v0[1] * v0[1]) + (v0[2] * v0[2] + v0[3] * v0[3])) + ((v1[0] * v1[0] + v1[1] * v1[1]) + (v1[2] * v1[2] + v1[3] * v1[3]));
;                     u32x4 w; w.x = cvt_pk_bf16(v0[0], v0[1]); w.y = cvt_pk_bf16(v0[2], v0[3]); w.z = cvt_pk_bf16(v1[0], v1[1]); w.w = cvt_pk_bf16(v1[2], v1[3]);
;                     *(u32x4*)(out + off) = w;
;                 }
;                 q += __shfl_xor(q, 1); q += __shfl_xor(q, 2);
;                 if (p == 0) atomicAdd(ssn + row, (u64)(q * SS_SCALE));
.LBB0_952:
	ds_write_b128 v156, v[124:127]
	ds_write_b128 v156, v[120:123] offset:64
	ds_read_b128 v[120:123], v157
	ds_read_b128 v[124:127], v157 offset:16
	ds_write_b128 v156, v[116:119]
	ds_write_b128 v156, v[112:115] offset:64
	ds_read_b128 v[112:115], v157
	ds_read_b128 v[116:119], v157 offset:16
	s_waitcnt vmcnt(15) lgkmcnt(4)
	v_lshlrev_b32_e32 v236, 16, v160
	v_and_b32_e32 v237, 0xffff0000, v160
	v_lshlrev_b32_e32 v238, 16, v161
	v_and_b32_e32 v239, 0xffff0000, v161
	v_lshlrev_b32_e32 v240, 16, v162
	v_and_b32_e32 v241, 0xffff0000, v162
	v_lshlrev_b32_e32 v242, 16, v163
	v_and_b32_e32 v243, 0xffff0000, v163
	v_pk_add_f32 v[120:121], v[120:121], v[236:237]
	v_pk_add_f32 v[122:123], v[122:123], v[238:239]
	v_pk_add_f32 v[124:125], v[124:125], v[240:241]
	v_pk_add_f32 v[126:127], v[126:127], v[242:243]
	v_mul_f32_e32 v236, v121, v121
	v_mul_f32_e32 v237, v123, v123
	v_mul_f32_e32 v238, v125, v125
	v_mul_f32_e32 v239, v127, v127
	v_fmac_f32_e32 v236, v120, v120
	v_fmac_f32_e32 v237, v122, v122
	v_fmac_f32_e32 v238, v124, v124
	v_fmac_f32_e32 v239, v126, v126
	v_cvt_pk_bf16_f32 v120, v120, v121
	v_cvt_pk_bf16_f32 v121, v122, v123
	v_cvt_pk_bf16_f32 v122, v124, v125
	v_cvt_pk_bf16_f32 v123, v126, v127
	v_add_f32_e32 v236, v236, v237
	v_add_f32_e32 v237, v238, v239
	v_add_f32_e32 v124, v236, v237
	global_store_dwordx4 v159, v[120:123], s[28:29]
	ds_write_b128 v156, v[108:111]
	ds_write_b128 v156, v[104:107] offset:64
	ds_read_b128 v[104:107], v157
	ds_read_b128 v[108:111], v157 offset:16
	s_waitcnt vmcnt(15) lgkmcnt(4)
	v_lshlrev_b32_e32 v236, 16, v164
	v_and_b32_e32 v237, 0xffff0000, v164
	v_lshlrev_b32_e32 v238, 16, v165
	v_and_b32_e32 v239, 0xffff0000, v165
	v_lshlrev_b32_e32 v240, 16, v166
	v_and_b32_e32 v241, 0xffff0000, v166
	v_lshlrev_b32_e32 v242, 16, v167
	v_and_b32_e32 v243, 0xffff0000, v167
	v_pk_add_f32 v[112:113], v[112:113], v[236:237]
	v_pk_add_f32 v[114:115], v[114:115], v[238:239]
	v_pk_add_f32 v[116:117], v[116:117], v[240:241]
	v_pk_add_f32 v[118:119], v[118:119], v[242:243]
	v_mul_f32_e32 v236, v113, v113
	v_mul_f32_e32 v237, v115, v115
	v_mul_f32_e32 v238, v117, v117
	v_mul_f32_e32 v239, v119, v119
	v_fmac_f32_e32 v236, v112, v112
	v_fmac_f32_e32 v237, v114, v114
	v_fmac_f32_e32 v238, v116, v116
	v_fmac_f32_e32 v239, v118, v118
	v_cvt_pk_bf16_f32 v112, v112, v113
	v_cvt_pk_bf16_f32 v113, v114, v115
	v_cvt_pk_bf16_f32 v114, v116, v117
	v_cvt_pk_bf16_f32 v115, v118, v119
	v_add_f32_e32 v236, v236, v237
	v_add_f32_e32 v237, v238, v239
	v_add_f32_e32 v116, v236, v237
	global_store_dwordx4 v159, v[112:115], s[28:29] offset:64
	v_add_f32_e32 v117, v124, v116
	s_nop 1
	v_add_f32_dpp v118, v117, v117 quad_perm:[1,0,3,2] row_mask:0xf bank_mask:0xf
	s_nop 1
	v_add_f32_dpp v119, v118, v118 quad_perm:[2,3,0,1] row_mask:0xf bank_mask:0xf
	v_mul_f32_e32 v126, 0x49800000, v119
	v_trunc_f32_e32 v126, v126
	v_mul_f32_e32 v127, 0x2f800000, v126
	v_floor_f32_e32 v127, v127
	v_fmac_f32_e32 v126, 0xcf800000, v127
	v_cvt_u32_f32_e32 v126, v126
	v_cvt_u32_f32_e32 v127, v127
	ds_write_b128 v156, v[100:103]
	ds_write_b128 v156, v[96:99] offset:64
	ds_read_b128 v[96:99], v157
	ds_read_b128 v[100:103], v157 offset:16
	s_waitcnt vmcnt(15) lgkmcnt(4)
	v_lshlrev_b32_e32 v236, 16, v168
	v_and_b32_e32 v237, 0xffff0000, v168
	v_lshlrev_b32_e32 v238, 16, v169
	v_and_b32_e32 v239, 0xffff0000, v169
	v_lshlrev_b32_e32 v240, 16, v170
	v_and_b32_e32 v241, 0xffff0000, v170
	v_lshlrev_b32_e32 v242, 16, v171
	v_and_b32_e32 v243, 0xffff0000, v171
	v_pk_add_f32 v[104:105], v[104:105], v[236:237]
	v_pk_add_f32 v[106:107], v[106:107], v[238:239]
	v_pk_add_f32 v[108:109], v[108:109], v[240:241]
	v_pk_add_f32 v[110:111], v[110:111], v[242:243]
	v_mul_f32_e32 v236, v105, v105
	v_mul_f32_e32 v237, v107, v107
	v_mul_f32_e32 v238, v109, v109
	v_mul_f32_e32 v239, v111, v111
	v_fmac_f32_e32 v236, v104, v104
	v_fmac_f32_e32 v237, v106, v106
	v_fmac_f32_e32 v238, v108, v108
	v_fmac_f32_e32 v239, v110, v110
	v_cvt_pk_bf16_f32 v104, v104, v105
	v_cvt_pk_bf16_f32 v105, v106, v107
	v_cvt_pk_bf16_f32 v106, v108, v109
	v_cvt_pk_bf16_f32 v107, v110, v111
	v_add_f32_e32 v236, v236, v237
	v_add_f32_e32 v237, v238, v239
	v_add_f32_e32 v108, v236, v237
	v_add_u32_e32 v147, 0x10000, v159
	global_store_dwordx4 v147, v[104:107], s[28:29]
	ds_write_b128 v156, v[92:95]
	ds_write_b128 v156, v[88:91] offset:64
	ds_read_b128 v[88:91], v157
	ds_read_b128 v[92:95], v157 offset:16
	s_waitcnt vmcnt(15) lgkmcnt(4)
	v_lshlrev_b32_e32 v236, 16, v172
	v_and_b32_e32 v237, 0xffff0000, v172
	v_lshlrev_b32_e32 v238, 16, v173
	v_and_b32_e32 v239, 0xffff0000, v173
	v_lshlrev_b32_e32 v240, 16, v174
	v_and_b32_e32 v241, 0xffff0000, v174
	v_lshlrev_b32_e32 v242, 16, v175
	v_and_b32_e32 v243, 0xffff0000, v175
	v_pk_add_f32 v[96:97], v[96:97], v[236:237]
	v_pk_add_f32 v[98:99], v[98:99], v[238:239]
	v_pk_add_f32 v[100:101], v[100:101], v[240:241]
	v_pk_add_f32 v[102:103], v[102:103], v[242:243]
	v_mul_f32_e32 v236, v97, v97
	v_mul_f32_e32 v237, v99, v99
	v_mul_f32_e32 v238, v101, v101
	v_mul_f32_e32 v239, v103, v103
	v_fmac_f32_e32 v236, v96, v96
	v_fmac_f32_e32 v237, v98, v98
	v_fmac_f32_e32 v238, v100, v100
	v_fmac_f32_e32 v239, v102, v102
	v_cvt_pk_bf16_f32 v96, v96, v97
	v_cvt_pk_bf16_f32 v97, v98, v99
	v_cvt_pk_bf16_f32 v98, v100, v101
	v_cvt_pk_bf16_f32 v99, v102, v103
	v_add_f32_e32 v236, v236, v237
	v_add_f32_e32 v237, v238, v239
	v_add_f32_e32 v100, v236, v237
	global_store_dwordx4 v147, v[96:99], s[28:29] offset:64
	v_add_f32_e32 v101, v108, v100
	s_nop 1
	v_add_f32_dpp v102, v101, v101 quad_perm:[1,0,3,2] row_mask:0xf bank_mask:0xf
	s_nop 1
	v_add_f32_dpp v103, v102, v102 quad_perm:[2,3,0,1] row_mask:0xf bank_mask:0xf
	v_mul_f32_e32 v110, 0x49800000, v103
	v_trunc_f32_e32 v110, v110
	v_mul_f32_e32 v111, 0x2f800000, v110
	v_floor_f32_e32 v111, v111
	v_fmac_f32_e32 v110, 0xcf800000, v111
	v_cvt_u32_f32_e32 v110, v110
	v_cvt_u32_f32_e32 v111, v111
	ds_write_b128 v156, v[84:87]
	ds_write_b128 v156, v[80:83] offset:64
	ds_read_b128 v[80:83], v157
	ds_read_b128 v[84:87], v157 offset:16
	s_waitcnt vmcnt(15) lgkmcnt(4)
; #define PG8_LAS __attribute__((address_space(3)))
; __device__ __forceinline__ unsigned cvt_pk_bf16(float lo, float hi) { unsigned r; asm volatile("v_cvt_pk_bf16_f32 %0, %1, %2" : "=v"(r) : "v"(lo), "v"(hi)); return r; }
;     __device__ __forceinline__ void operator()(const f32x4 (&acc)[2][2][4][2], const Unit& u, int wr, int wc, int fr, int fq) const {
;     ...
;                 for (int bj = 0; bj < 2; ++bj) {
;                     const size_t off = (size_t)row * 2048 + u.pn * BM + wc * 64 + bj * 32 + 8 * p;
;                     f32x4 b0, b1;
;                     if (BASE_F32) { b0 = *(const f32x4*)((const float*)base + off); b1 = *(const f32x4*)((const float*)base + off + 4); }
;                     else { const u32x4 bb = *(const u32x4*)((const bf16_t*)base + off);
;                         b0 = (f32x4){__uint_as_float(bb.x << 16), __uint_as_float(bb.x & 0xffff0000u), __uint_as_float(bb.y << 16), __uint_as_float(bb.y & 0xffff0000u)};
;                         b1 = (f32x4){__uint_as_float(bb.z << 16), __uint_as_float(bb.z & 0xffff0000u), __uint_as_float(bb.w << 16), __uint_as_float(bb.w & 0xffff0000u)}; }
; #pragma unroll
;                     for (int n = 0; n < 2; ++n) *(PG8_LAS f32x4*)(stg + fr * STG_ROW + n * 64 + fq * 16) = acc[ai][bj][m][n];
;                     const f32x4 v0 = *(const PG8_LAS f32x4*)(stg + r * STG_ROW + p * 32) + b0, v1 = *(const PG8_LAS f32x4*)(stg + r * STG_ROW + p * 32 + 16) + b1;
;                     q += ((v0[0] * v0[0] + v0[1] * v0[1]) + (v0[2] * v0[2] + v0[3] * v0[3])) + ((v1[0] * v1[0] + v1[1] * v1[1]) + (v1[2] * v1[2] + v1[3] * v1[3]));
;                     u32x4 w; w.x = cvt_pk_bf16(v0[0], v0[1]); w.y = cvt_pk_bf16(v0[2], v0[3]); w.z = cvt_pk_bf16(v1[0], v1[1]); w.w = cvt_pk_bf16(v1[2], v1[3]);
;                     *(u32x4*)(out + off) = w;
;                 }
;                 q += __shfl_xor(q, 1); q += __shfl_xor(q, 2);
;                 if (p == 0) atomicAdd(ssn + row, (u64)(q * SS_SCALE));
	v_lshlrev_b32_e32 v236, 16, v176
	v_and_b32_e32 v237, 0xffff0000, v176
	v_lshlrev_b32_e32 v238, 16, v177
	v_and_b32_e32 v239, 0xffff0000, v177
	v_lshlrev_b32_e32 v240, 16, v178
	v_and_b32_e32 v241, 0xffff0000, v178
	v_lshlrev_b32_e32 v242, 16, v179
	v_and_b32_e32 v243, 0xffff0000, v179
	v_pk_add_f32 v[88:89], v[88:89], v[236:237]
	v_pk_add_f32 v[90:91], v[90:91], v[238:239]
	v_pk_add_f32 v[92:93], v[92:93], v[240:241]
	v_pk_add_f32 v[94:95], v[94:95], v[242:243]
	v_mul_f32_e32 v236, v89, v89
	v_mul_f32_e32 v237, v91, v91
	v_mul_f32_e32 v238, v93, v93
	v_mul_f32_e32 v239, v95, v95
	v_fmac_f32_e32 v236, v88, v88
	v_fmac_f32_e32 v237, v90, v90
	v_fmac_f32_e32 v238, v92, v92
	v_fmac_f32_e32 v239, v94, v94
	v_cvt_pk_bf16_f32 v88, v88, v89
	v_cvt_pk_bf16_f32 v89, v90, v91
	v_cvt_pk_bf16_f32 v90, v92, v93
	v_cvt_pk_bf16_f32 v91, v94, v95
	v_add_f32_e32 v236, v236, v237
	v_add_f32_e32 v237, v238, v239
	v_add_f32_e32 v92, v236, v237
	v_add_u32_e32 v146, 0x20000, v159
	global_store_dwordx4 v146, v[88:91], s[28:29]
	ds_write_b128 v156, v[76:79]
	ds_write_b128 v156, v[72:75] offset:64
	ds_read_b128 v[72:75], v157
	ds_read_b128 v[76:79], v157 offset:16
	s_waitcnt vmcnt(15) lgkmcnt(4)
	v_lshlrev_b32_e32 v236, 16, v180
	v_and_b32_e32 v237, 0xffff0000, v180
	v_lshlrev_b32_e32 v238, 16, v181
	v_and_b32_e32 v239, 0xffff0000, v181
	v_lshlrev_b32_e32 v240, 16, v182
	v_and_b32_e32 v241, 0xffff0000, v182
	v_lshlrev_b32_e32 v242, 16, v183
	v_and_b32_e32 v243, 0xffff0000, v183
	v_pk_add_f32 v[80:81], v[80:81], v[236:237]
	v_pk_add_f32 v[82:83], v[82:83], v[238:239]
	v_pk_add_f32 v[84:85], v[84:85], v[240:241]
	v_pk_add_f32 v[86:87], v[86:87], v[242:243]
	v_mul_f32_e32 v236, v81, v81
	v_mul_f32_e32 v237, v83, v83
	v_mul_f32_e32 v238, v85, v85
	v_mul_f32_e32 v239, v87, v87
	v_fmac_f32_e32 v236, v80, v80
	v_fmac_f32_e32 v237, v82, v82
	v_fmac_f32_e32 v238, v84, v84
	v_fmac_f32_e32 v239, v86, v86
	v_cvt_pk_bf16_f32 v80, v80, v81
	v_cvt_pk_bf16_f32 v81, v82, v83
	v_cvt_pk_bf16_f32 v82, v84, v85
	v_cvt_pk_bf16_f32 v83, v86, v87
	v_add_f32_e32 v236, v236, v237
	v_add_f32_e32 v237, v238, v239
	v_add_f32_e32 v84, v236, v237
	global_store_dwordx4 v146, v[80:83], s[28:29] offset:64
	v_add_f32_e32 v85, v92, v84
	s_nop 1
	v_add_f32_dpp v86, v85, v85 quad_perm:[1,0,3,2] row_mask:0xf bank_mask:0xf
	s_nop 1
	v_add_f32_dpp v87, v86, v86 quad_perm:[2,3,0,1] row_mask:0xf bank_mask:0xf
	v_mul_f32_e32 v94, 0x49800000, v87
	v_trunc_f32_e32 v94, v94
	v_mul_f32_e32 v95, 0x2f800000, v94
	v_floor_f32_e32 v95, v95
	v_fmac_f32_e32 v94, 0xcf800000, v95
	v_cvt_u32_f32_e32 v94, v94
	v_cvt_u32_f32_e32 v95, v95
	ds_write_b128 v156, v[68:71]
	ds_write_b128 v156, v[64:67] offset:64
	ds_read_b128 v[64:67], v157
	ds_read_b128 v[68:71], v157 offset:16
	s_waitcnt vmcnt(15) lgkmcnt(4)
	v_lshlrev_b32_e32 v236, 16, v184
	v_and_b32_e32 v237, 0xffff0000, v184
	v_lshlrev_b32_e32 v238, 16, v185
	v_and_b32_e32 v239, 0xffff0000, v185
	v_lshlrev_b32_e32 v240, 16, v186
	v_and_b32_e32 v241, 0xffff0000, v186
	v_lshlrev_b32_e32 v242, 16, v187
	v_and_b32_e32 v243, 0xffff0000, v187
	v_pk_add_f32 v[72:73], v[72:73], v[236:237]
	v_pk_add_f32 v[74:75], v[74:75], v[238:239]
	v_pk_add_f32 v[76:77], v[76:77], v[240:241]
	v_pk_add_f32 v[78:79], v[78:79], v[242:243]
	v_mul_f32_e32 v236, v73, v73
	v_mul_f32_e32 v237, v75, v75
	v_mul_f32_e32 v238, v77, v77
	v_mul_f32_e32 v239, v79, v79
	v_fmac_f32_e32 v236, v72, v72
	v_fmac_f32_e32 v237, v74, v74
	v_fmac_f32_e32 v238, v76, v76
	v_fmac_f32_e32 v239, v78, v78
	v_cvt_pk_bf16_f32 v72, v72, v73
	v_cvt_pk_bf16_f32 v73, v74, v75
	v_cvt_pk_bf16_f32 v74, v76, v77
	v_cvt_pk_bf16_f32 v75, v78, v79
	v_add_f32_e32 v236, v236, v237
	v_add_f32_e32 v237, v238, v239
	v_add_f32_e32 v76, v236, v237
	v_add_u32_e32 v147, 0x30000, v159
	global_store_dwordx4 v147, v[72:75], s[28:29]
	ds_write_b128 v156, v[60:63]
	ds_write_b128 v156, v[56:59] offset:64
	ds_read_b128 v[56:59], v157
	ds_read_b128 v[60:63], v157 offset:16
	s_waitcnt vmcnt(15) lgkmcnt(4)
	v_lshlrev_b32_e32 v236, 16, v188
	v_and_b32_e32 v237, 0xffff0000, v188
	v_lshlrev_b32_e32 v238, 16, v189
	v_and_b32_e32 v239, 0xffff0000, v189
	v_lshlrev_b32_e32 v240, 16, v190
	v_and_b32_e32 v241, 0xffff0000, v190
	v_lshlrev_b32_e32 v242, 16, v191
	v_and_b32_e32 v243, 0xffff0000, v191
	v_pk_add_f32 v[64:65], v[64:65], v[236:237]
	v_pk_add_f32 v[66:67], v[66:67], v[238:239]
	v_pk_add_f32 v[68:69], v[68:69], v[240:241]
	v_pk_add_f32 v[70:71], v[70:71], v[242:243]
	v_mul_f32_e32 v236, v65, v65
	v_mul_f32_e32 v237, v67, v67
	v_mul_f32_e32 v238, v69, v69
	v_mul_f32_e32 v239, v71, v71
	v_fmac_f32_e32 v236, v64, v64
	v_fmac_f32_e32 v237, v66, v66
	v_fmac_f32_e32 v238, v68, v68
	v_fmac_f32_e32 v239, v70, v70
	v_cvt_pk_bf16_f32 v64, v64, v65
	v_cvt_pk_bf16_f32 v65, v66, v67
	v_cvt_pk_bf16_f32 v66, v68, v69
	v_cvt_pk_bf16_f32 v67, v70, v71
	v_add_f32_e32 v236, v236, v237
	v_add_f32_e32 v237, v238, v239
	v_add_f32_e32 v68, v236, v237
	global_store_dwordx4 v147, v[64:67], s[28:29] offset:64
	v_add_f32_e32 v69, v76, v68
	s_nop 1
	v_add_f32_dpp v70, v69, v69 quad_perm:[1,0,3,2] row_mask:0xf bank_mask:0xf
	s_nop 1
	v_add_f32_dpp v71, v70, v70 quad_perm:[2,3,0,1] row_mask:0xf bank_mask:0xf
	v_mul_f32_e32 v78, 0x49800000, v71
	v_trunc_f32_e32 v78, v78
	v_mul_f32_e32 v79, 0x2f800000, v78
	v_floor_f32_e32 v79, v79
	v_fmac_f32_e32 v78, 0xcf800000, v79
	v_cvt_u32_f32_e32 v78, v78
	v_cvt_u32_f32_e32 v79, v79
	ds_write_b128 v156, v[52:55]
	ds_write_b128 v156, v[48:51] offset:64
	ds_read_b128 v[48:51], v157
	ds_read_b128 v[52:55], v157 offset:16
	s_waitcnt vmcnt(15) lgkmcnt(4)
; #define PG8_LAS __attribute__((address_space(3)))
; __device__ __forceinline__ unsigned cvt_pk_bf16(float lo, float hi) { unsigned r; asm volatile("v_cvt_pk_bf16_f32 %0, %1, %2" : "=v"(r) : "v"(lo), "v"(hi)); return r; }
;     __device__ __forceinline__ void operator()(const f32x4 (&acc)[2][2][4][2], const Unit& u, int wr, int wc, int fr, int fq) const {
;     ...
;                 for (int bj = 0; bj < 2; ++bj) {
;                     const size_t off = (size_t)row * 2048 + u.pn * BM + wc * 64 + bj * 32 + 8 * p;
;                     f32x4 b0, b1;
;                     if (BASE_F32) { b0 = *(const f32x4*)((const float*)base + off); b1 = *(const f32x4*)((const float*)base + off + 4); }
;                     else { const u32x4 bb = *(const u32x4*)((const bf16_t*)base + off);
;                         b0 = (f32x4){__uint_as_float(bb.x << 16), __uint_as_float(bb.x & 0xffff0000u), __uint_as_float(bb.y << 16), __uint_as_float(bb.y & 0xffff0000u)};
;                         b1 = (f32x4){__uint_as_float(bb.z << 16), __uint_as_float(bb.z & 0xffff0000u), __uint_as_float(bb.w << 16), __uint_as_float(bb.w & 0xffff0000u)}; }
; #pragma unroll
;                     for (int n = 0; n < 2; ++n) *(PG8_LAS f32x4*)(stg + fr * STG_ROW + n * 64 + fq * 16) = acc[ai][bj][m][n];
;                     const f32x4 v0 = *(const PG8_LAS f32x4*)(stg + r * STG_ROW + p * 32) + b0, v1 = *(const PG8_LAS f32x4*)(stg + r * STG_ROW + p * 32 + 16) + b1;
;                     q += ((v0[0] * v0[0] + v0[1] * v0[1]) + (v0[2] * v0[2] + v0[3] * v0[3])) + ((v1[0] * v1[0] + v1[1] * v1[1]) + (v1[2] * v1[2] + v1[3] * v1[3]));
;                     u32x4 w; w.x = cvt_pk_bf16(v0[0], v0[1]); w.y = cvt_pk_bf16(v0[2], v0[3]); w.z = cvt_pk_bf16(v1[0], v1[1]); w.w = cvt_pk_bf16(v1[2], v1[3]);
;                     *(u32x4*)(out + off) = w;
;                 }
;                 q += __shfl_xor(q, 1); q += __shfl_xor(q, 2);
;                 if (p == 0) atomicAdd(ssn + row, (u64)(q * SS_SCALE));
	v_lshlrev_b32_e32 v236, 16, v192
	v_and_b32_e32 v237, 0xffff0000, v192
	v_lshlrev_b32_e32 v238, 16, v193
	v_and_b32_e32 v239, 0xffff0000, v193
	v_lshlrev_b32_e32 v240, 16, v194
	v_and_b32_e32 v241, 0xffff0000, v194
	v_lshlrev_b32_e32 v242, 16, v195
	v_and_b32_e32 v243, 0xffff0000, v195
	v_pk_add_f32 v[56:57], v[56:57], v[236:237]
	v_pk_add_f32 v[58:59], v[58:59], v[238:239]
	v_pk_add_f32 v[60:61], v[60:61], v[240:241]
	v_pk_add_f32 v[62:63], v[62:63], v[242:243]
	v_mul_f32_e32 v236, v57, v57
	v_mul_f32_e32 v237, v59, v59
	v_mul_f32_e32 v238, v61, v61
	v_mul_f32_e32 v239, v63, v63
	v_fmac_f32_e32 v236, v56, v56
	v_fmac_f32_e32 v237, v58, v58
	v_fmac_f32_e32 v238, v60, v60
	v_fmac_f32_e32 v239, v62, v62
	v_cvt_pk_bf16_f32 v56, v56, v57
	v_cvt_pk_bf16_f32 v57, v58, v59
	v_cvt_pk_bf16_f32 v58, v60, v61
	v_cvt_pk_bf16_f32 v59, v62, v63
	v_add_f32_e32 v236, v236, v237
	v_add_f32_e32 v237, v238, v239
	v_add_f32_e32 v60, v236, v237
	v_add_u32_e32 v146, 0x80000, v159
	global_store_dwordx4 v146, v[56:59], s[28:29]
	ds_write_b128 v156, v[44:47]
	ds_write_b128 v156, v[40:43] offset:64
	ds_read_b128 v[40:43], v157
	ds_read_b128 v[44:47], v157 offset:16
	s_waitcnt vmcnt(15) lgkmcnt(4)
	v_lshlrev_b32_e32 v236, 16, v196
	v_and_b32_e32 v237, 0xffff0000, v196
	v_lshlrev_b32_e32 v238, 16, v197
	v_and_b32_e32 v239, 0xffff0000, v197
	v_lshlrev_b32_e32 v240, 16, v198
	v_and_b32_e32 v241, 0xffff0000, v198
	v_lshlrev_b32_e32 v242, 16, v199
	v_and_b32_e32 v243, 0xffff0000, v199
	v_pk_add_f32 v[48:49], v[48:49], v[236:237]
	v_pk_add_f32 v[50:51], v[50:51], v[238:239]
	v_pk_add_f32 v[52:53], v[52:53], v[240:241]
	v_pk_add_f32 v[54:55], v[54:55], v[242:243]
	v_mul_f32_e32 v236, v49, v49
	v_mul_f32_e32 v237, v51, v51
	v_mul_f32_e32 v238, v53, v53
	v_mul_f32_e32 v239, v55, v55
	v_fmac_f32_e32 v236, v48, v48
	v_fmac_f32_e32 v237, v50, v50
	v_fmac_f32_e32 v238, v52, v52
	v_fmac_f32_e32 v239, v54, v54
	v_cvt_pk_bf16_f32 v48, v48, v49
	v_cvt_pk_bf16_f32 v49, v50, v51
	v_cvt_pk_bf16_f32 v50, v52, v53
	v_cvt_pk_bf16_f32 v51, v54, v55
	v_add_f32_e32 v236, v236, v237
	v_add_f32_e32 v237, v238, v239
	v_add_f32_e32 v52, v236, v237
	global_store_dwordx4 v146, v[48:51], s[28:29] offset:64
	v_add_f32_e32 v53, v60, v52
	s_nop 1
	v_add_f32_dpp v54, v53, v53 quad_perm:[1,0,3,2] row_mask:0xf bank_mask:0xf
	s_nop 1
	v_add_f32_dpp v55, v54, v54 quad_perm:[2,3,0,1] row_mask:0xf bank_mask:0xf
	v_mul_f32_e32 v62, 0x49800000, v55
	v_trunc_f32_e32 v62, v62
	v_mul_f32_e32 v63, 0x2f800000, v62
	v_floor_f32_e32 v63, v63
	v_fmac_f32_e32 v62, 0xcf800000, v63
	v_cvt_u32_f32_e32 v62, v62
	v_cvt_u32_f32_e32 v63, v63
	ds_write_b128 v156, v[36:39]
	ds_write_b128 v156, v[32:35] offset:64
	ds_read_b128 v[32:35], v157
	ds_read_b128 v[36:39], v157 offset:16
	s_waitcnt vmcnt(15) lgkmcnt(4)
	v_lshlrev_b32_e32 v236, 16, v200
	v_and_b32_e32 v237, 0xffff0000, v200
	v_lshlrev_b32_e32 v238, 16, v201
	v_and_b32_e32 v239, 0xffff0000, v201
	v_lshlrev_b32_e32 v240, 16, v202
	v_and_b32_e32 v241, 0xffff0000, v202
	v_lshlrev_b32_e32 v242, 16, v203
	v_and_b32_e32 v243, 0xffff0000, v203
	v_pk_add_f32 v[40:41], v[40:41], v[236:237]
	v_pk_add_f32 v[42:43], v[42:43], v[238:239]
	v_pk_add_f32 v[44:45], v[44:45], v[240:241]
	v_pk_add_f32 v[46:47], v[46:47], v[242:243]
	v_mul_f32_e32 v236, v41, v41
	v_mul_f32_e32 v237, v43, v43
	v_mul_f32_e32 v238, v45, v45
	v_mul_f32_e32 v239, v47, v47
	v_fmac_f32_e32 v236, v40, v40
	v_fmac_f32_e32 v237, v42, v42
	v_fmac_f32_e32 v238, v44, v44
	v_fmac_f32_e32 v239, v46, v46
	v_cvt_pk_bf16_f32 v40, v40, v41
	v_cvt_pk_bf16_f32 v41, v42, v43
	v_cvt_pk_bf16_f32 v42, v44, v45
	v_cvt_pk_bf16_f32 v43, v46, v47
	v_add_f32_e32 v236, v236, v237
	v_add_f32_e32 v237, v238, v239
	v_add_f32_e32 v44, v236, v237
	v_add_u32_e32 v147, 0x90000, v159
	global_store_dwordx4 v147, v[40:43], s[28:29]
	ds_write_b128 v156, v[28:31]
	ds_write_b128 v156, v[24:27] offset:64
	ds_read_b128 v[24:27], v157
	ds_read_b128 v[28:31], v157 offset:16
	s_waitcnt vmcnt(15) lgkmcnt(4)
	v_lshlrev_b32_e32 v236, 16, v204
	v_and_b32_e32 v237, 0xffff0000, v204
	v_lshlrev_b32_e32 v238, 16, v205
	v_and_b32_e32 v239, 0xffff0000, v205
	v_lshlrev_b32_e32 v240, 16, v206
	v_and_b32_e32 v241, 0xffff0000, v206
	v_lshlrev_b32_e32 v242, 16, v207
	v_and_b32_e32 v243, 0xffff0000, v207
	v_pk_add_f32 v[32:33], v[32:33], v[236:237]
	v_pk_add_f32 v[34:35], v[34:35], v[238:239]
	v_pk_add_f32 v[36:37], v[36:37], v[240:241]
	v_pk_add_f32 v[38:39], v[38:39], v[242:243]
	v_mul_f32_e32 v236, v33, v33
	v_mul_f32_e32 v237, v35, v35
	v_mul_f32_e32 v238, v37, v37
	v_mul_f32_e32 v239, v39, v39
	v_fmac_f32_e32 v236, v32, v32
	v_fmac_f32_e32 v237, v34, v34
	v_fmac_f32_e32 v238, v36, v36
	v_fmac_f32_e32 v239, v38, v38
	v_cvt_pk_bf16_f32 v32, v32, v33
	v_cvt_pk_bf16_f32 v33, v34, v35
	v_cvt_pk_bf16_f32 v34, v36, v37
	v_cvt_pk_bf16_f32 v35, v38, v39
	v_add_f32_e32 v236, v236, v237
	v_add_f32_e32 v237, v238, v239
	v_add_f32_e32 v36, v236, v237
	global_store_dwordx4 v147, v[32:35], s[28:29] offset:64
	v_add_f32_e32 v37, v44, v36
	s_nop 1
	v_add_f32_dpp v38, v37, v37 quad_perm:[1,0,3,2] row_mask:0xf bank_mask:0xf
	s_nop 1
	v_add_f32_dpp v39, v38, v38 quad_perm:[2,3,0,1] row_mask:0xf bank_mask:0xf
	v_mul_f32_e32 v46, 0x49800000, v39
	v_trunc_f32_e32 v46, v46
	v_mul_f32_e32 v47, 0x2f800000, v46
	v_floor_f32_e32 v47, v47
	v_fmac_f32_e32 v46, 0xcf800000, v47
	v_cvt_u32_f32_e32 v46, v46
	v_cvt_u32_f32_e32 v47, v47
	ds_write_b128 v156, v[20:23]
	ds_write_b128 v156, v[16:19] offset:64
	ds_read_b128 v[16:19], v157
	ds_read_b128 v[20:23], v157 offset:16
	s_waitcnt vmcnt(15) lgkmcnt(4)
; #define PG8_LAS __attribute__((address_space(3)))
; __device__ __forceinline__ unsigned cvt_pk_bf16(float lo, float hi) { unsigned r; asm volatile("v_cvt_pk_bf16_f32 %0, %1, %2" : "=v"(r) : "v"(lo), "v"(hi)); return r; }
;     __device__ __forceinline__ void operator()(const f32x4 (&acc)[2][2][4][2], const Unit& u, int wr, int wc, int fr, int fq) const {
;     ...
;                 for (int bj = 0; bj < 2; ++bj) {
;                     const size_t off = (size_t)row * 2048 + u.pn * BM + wc * 64 + bj * 32 + 8 * p;
;                     f32x4 b0, b1;
;                     if (BASE_F32) { b0 = *(const f32x4*)((const float*)base + off); b1 = *(const f32x4*)((const float*)base + off + 4); }
;                     else { const u32x4 bb = *(const u32x4*)((const bf16_t*)base + off);
;                         b0 = (f32x4){__uint_as_float(bb.x << 16), __uint_as_float(bb.x & 0xffff0000u), __uint_as_float(bb.y << 16), __uint_as_float(bb.y & 0xffff0000u)};
;                         b1 = (f32x4){__uint_as_float(bb.z << 16), __uint_as_float(bb.z & 0xffff0000u), __uint_as_float(bb.w << 16), __uint_as_float(bb.w & 0xffff0000u)}; }
; #pragma unroll
;                     for (int n = 0; n < 2; ++n) *(PG8_LAS f32x4*)(stg + fr * STG_ROW + n * 64 + fq * 16) = acc[ai][bj][m][n];
;                     const f32x4 v0 = *(const PG8_LAS f32x4*)(stg + r * STG_ROW + p * 32) + b0, v1 = *(const PG8_LAS f32x4*)(stg + r * STG_ROW + p * 32 + 16) + b1;
;                     q += ((v0[0] * v0[0] + v0[1] * v0[1]) + (v0[2] * v0[2] + v0[3] * v0[3])) + ((v1[0] * v1[0] + v1[1] * v1[1]) + (v1[2] * v1[2] + v1[3] * v1[3]));
;                     u32x4 w; w.x = cvt_pk_bf16(v0[0], v0[1]); w.y = cvt_pk_bf16(v0[2], v0[3]); w.z = cvt_pk_bf16(v1[0], v1[1]); w.w = cvt_pk_bf16(v1[2], v1[3]);
;                     *(u32x4*)(out + off) = w;
;                 }
;                 q += __shfl_xor(q, 1); q += __shfl_xor(q, 2);
;                 if (p == 0) atomicAdd(ssn + row, (u64)(q * SS_SCALE));
	v_lshlrev_b32_e32 v236, 16, v212
	v_and_b32_e32 v237, 0xffff0000, v212
	v_lshlrev_b32_e32 v238, 16, v213
	v_and_b32_e32 v239, 0xffff0000, v213
	v_lshlrev_b32_e32 v240, 16, v214
	v_and_b32_e32 v241, 0xffff0000, v214
	v_lshlrev_b32_e32 v242, 16, v215
	v_and_b32_e32 v243, 0xffff0000, v215
	v_pk_add_f32 v[24:25], v[24:25], v[236:237]
	v_pk_add_f32 v[26:27], v[26:27], v[238:239]
	v_pk_add_f32 v[28:29], v[28:29], v[240:241]
	v_pk_add_f32 v[30:31], v[30:31], v[242:243]
	v_mul_f32_e32 v236, v25, v25
	v_mul_f32_e32 v237, v27, v27
	v_mul_f32_e32 v238, v29, v29
	v_mul_f32_e32 v239, v31, v31
	v_fmac_f32_e32 v236, v24, v24
	v_fmac_f32_e32 v237, v26, v26
	v_fmac_f32_e32 v238, v28, v28
	v_fmac_f32_e32 v239, v30, v30
	v_cvt_pk_bf16_f32 v24, v24, v25
	v_cvt_pk_bf16_f32 v25, v26, v27
	v_cvt_pk_bf16_f32 v26, v28, v29
	v_cvt_pk_bf16_f32 v27, v30, v31
	v_add_f32_e32 v236, v236, v237
	v_add_f32_e32 v237, v238, v239
	v_add_f32_e32 v28, v236, v237
	v_add_u32_e32 v146, 0xa0000, v159
	global_store_dwordx4 v146, v[24:27], s[28:29]
	ds_write_b128 v156, v[12:15]
	ds_write_b128 v156, v[8:11] offset:64
	ds_read_b128 v[8:11], v157
	ds_read_b128 v[12:15], v157 offset:16
	s_waitcnt vmcnt(15) lgkmcnt(4)
	v_lshlrev_b32_e32 v236, 16, v216
	v_and_b32_e32 v237, 0xffff0000, v216
	v_lshlrev_b32_e32 v238, 16, v217
	v_and_b32_e32 v239, 0xffff0000, v217
	v_lshlrev_b32_e32 v240, 16, v218
	v_and_b32_e32 v241, 0xffff0000, v218
	v_lshlrev_b32_e32 v242, 16, v219
	v_and_b32_e32 v243, 0xffff0000, v219
	v_pk_add_f32 v[16:17], v[16:17], v[236:237]
	v_pk_add_f32 v[18:19], v[18:19], v[238:239]
	v_pk_add_f32 v[20:21], v[20:21], v[240:241]
	v_pk_add_f32 v[22:23], v[22:23], v[242:243]
	v_mul_f32_e32 v236, v17, v17
	v_mul_f32_e32 v237, v19, v19
	v_mul_f32_e32 v238, v21, v21
	v_mul_f32_e32 v239, v23, v23
	v_fmac_f32_e32 v236, v16, v16
	v_fmac_f32_e32 v237, v18, v18
	v_fmac_f32_e32 v238, v20, v20
	v_fmac_f32_e32 v239, v22, v22
	v_cvt_pk_bf16_f32 v16, v16, v17
	v_cvt_pk_bf16_f32 v17, v18, v19
	v_cvt_pk_bf16_f32 v18, v20, v21
	v_cvt_pk_bf16_f32 v19, v22, v23
	v_add_f32_e32 v236, v236, v237
	v_add_f32_e32 v237, v238, v239
	v_add_f32_e32 v20, v236, v237
	global_store_dwordx4 v146, v[16:19], s[28:29] offset:64
	v_add_f32_e32 v21, v28, v20
	s_nop 1
	v_add_f32_dpp v22, v21, v21 quad_perm:[1,0,3,2] row_mask:0xf bank_mask:0xf
	s_nop 1
	v_add_f32_dpp v23, v22, v22 quad_perm:[2,3,0,1] row_mask:0xf bank_mask:0xf
	v_mul_f32_e32 v30, 0x49800000, v23
	v_trunc_f32_e32 v30, v30
	v_mul_f32_e32 v31, 0x2f800000, v30
	v_floor_f32_e32 v31, v31
	v_fmac_f32_e32 v30, 0xcf800000, v31
	v_cvt_u32_f32_e32 v30, v30
	v_cvt_u32_f32_e32 v31, v31
	ds_write_b128 v156, v[4:7]
	ds_write_b128 v156, v[0:3] offset:64
	ds_read_b128 v[0:3], v157
	ds_read_b128 v[4:7], v157 offset:16
	s_waitcnt vmcnt(15) lgkmcnt(4)
	v_lshlrev_b32_e32 v236, 16, v220
	v_and_b32_e32 v237, 0xffff0000, v220
	v_lshlrev_b32_e32 v238, 16, v221
	v_and_b32_e32 v239, 0xffff0000, v221
	v_lshlrev_b32_e32 v240, 16, v222
	v_and_b32_e32 v241, 0xffff0000, v222
	v_lshlrev_b32_e32 v242, 16, v223
	v_and_b32_e32 v243, 0xffff0000, v223
	v_pk_add_f32 v[8:9], v[8:9], v[236:237]
	v_pk_add_f32 v[10:11], v[10:11], v[238:239]
	v_pk_add_f32 v[12:13], v[12:13], v[240:241]
	v_pk_add_f32 v[14:15], v[14:15], v[242:243]
	v_mul_f32_e32 v236, v9, v9
	v_mul_f32_e32 v237, v11, v11
	v_mul_f32_e32 v238, v13, v13
	v_mul_f32_e32 v239, v15, v15
	v_fmac_f32_e32 v236, v8, v8
	v_fmac_f32_e32 v237, v10, v10
	v_fmac_f32_e32 v238, v12, v12
	v_fmac_f32_e32 v239, v14, v14
	v_cvt_pk_bf16_f32 v8, v8, v9
	v_cvt_pk_bf16_f32 v9, v10, v11
	v_cvt_pk_bf16_f32 v10, v12, v13
	v_cvt_pk_bf16_f32 v11, v14, v15
	v_add_f32_e32 v236, v236, v237
	v_add_f32_e32 v237, v238, v239
	v_add_f32_e32 v12, v236, v237
	v_add_u32_e32 v147, 0xb0000, v159
	global_store_dwordx4 v147, v[8:11], s[28:29]
	s_waitcnt vmcnt(15) lgkmcnt(0)
	v_lshlrev_b32_e32 v236, 16, v224
	v_and_b32_e32 v237, 0xffff0000, v224
	v_lshlrev_b32_e32 v238, 16, v225
	v_and_b32_e32 v239, 0xffff0000, v225
	v_lshlrev_b32_e32 v240, 16, v226
	v_and_b32_e32 v241, 0xffff0000, v226
	v_lshlrev_b32_e32 v242, 16, v227
	v_and_b32_e32 v243, 0xffff0000, v227
	v_pk_add_f32 v[0:1], v[0:1], v[236:237]
	v_pk_add_f32 v[2:3], v[2:3], v[238:239]
	v_pk_add_f32 v[4:5], v[4:5], v[240:241]
	v_pk_add_f32 v[6:7], v[6:7], v[242:243]
	v_mul_f32_e32 v236, v1, v1
	v_mul_f32_e32 v237, v3, v3
	v_mul_f32_e32 v238, v5, v5
	v_mul_f32_e32 v239, v7, v7
	v_fmac_f32_e32 v236, v0, v0
	v_fmac_f32_e32 v237, v2, v2
	v_fmac_f32_e32 v238, v4, v4
	v_fmac_f32_e32 v239, v6, v6
	v_cvt_pk_bf16_f32 v0, v0, v1
	v_cvt_pk_bf16_f32 v1, v2, v3
	v_cvt_pk_bf16_f32 v2, v4, v5
	v_cvt_pk_bf16_f32 v3, v6, v7
	v_add_f32_e32 v236, v236, v237
	v_add_f32_e32 v237, v238, v239
	v_add_f32_e32 v4, v236, v237
	global_store_dwordx4 v147, v[0:3], s[28:29] offset:64
	v_add_f32_e32 v5, v12, v4
	s_nop 1
	v_add_f32_dpp v6, v5, v5 quad_perm:[1,0,3,2] row_mask:0xf bank_mask:0xf
	s_nop 1
	v_add_f32_dpp v7, v6, v6 quad_perm:[2,3,0,1] row_mask:0xf bank_mask:0xf
	v_mul_f32_e32 v14, 0x49800000, v7
	v_trunc_f32_e32 v14, v14
	v_mul_f32_e32 v15, 0x2f800000, v14
	v_floor_f32_e32 v15, v15
	v_fmac_f32_e32 v14, 0xcf800000, v15
	v_cvt_u32_f32_e32 v14, v14
	v_cvt_u32_f32_e32 v15, v15
	v_and_b32_e32 v236, 3, v252
	v_lshl_add_u32 v237, v236, 7, v208
	v_cmp_eq_u32_e64 s[100:101], 1, v236
	s_nop 1
	v_cndmask_b32_e64 v126, v126, v110, s[100:101]
	v_cndmask_b32_e64 v127, v127, v111, s[100:101]
	v_cmp_eq_u32_e64 s[100:101], 2, v236
	s_nop 1
	v_cndmask_b32_e64 v126, v126, v94, s[100:101]
	v_cndmask_b32_e64 v127, v127, v95, s[100:101]
	v_cmp_eq_u32_e64 s[100:101], 3, v236
	s_nop 1
	v_cndmask_b32_e64 v126, v126, v78, s[100:101]
	v_cndmask_b32_e64 v127, v127, v79, s[100:101]
	global_atomic_add_x2 v237, v[126:127], s[12:13]
	v_cmp_eq_u32_e64 s[100:101], 1, v236
	s_nop 1
	v_cndmask_b32_e64 v62, v62, v46, s[100:101]
	v_cndmask_b32_e64 v63, v63, v47, s[100:101]
	v_cmp_eq_u32_e64 s[100:101], 2, v236
	s_nop 1
	v_cndmask_b32_e64 v62, v62, v30, s[100:101]
	v_cndmask_b32_e64 v63, v63, v31, s[100:101]
	v_cmp_eq_u32_e64 s[100:101], 3, v236
	s_nop 1
	v_cndmask_b32_e64 v62, v62, v14, s[100:101]
	v_cndmask_b32_e64 v63, v63, v15, s[100:101]
	global_atomic_add_x2 v237, v[62:63], s[12:13] offset:1024
	s_and_b64 vcc, exec, s[8:9]
	s_mov_b64 s[8:9], -1
	s_cbranch_vccnz .LBB0_939
	s_andn2_b64 vcc, exec, s[36:37]
	s_cbranch_vccnz .LBB0_938
	s_mov_b32 s98, 1
	s_branch .LBB0_938
